# GEMM K-loops: redundant post-barrier lgkmcnt(0) waits removed and vmcnt(8)+lgkmcnt(0) merged into one s_waitcnt; on top of no-setprio version
# speedup vs baseline: 1.0081x; 1.0023x over previous
;     DI bool next(int i, Unit& u) const { const long L = (long)i * G + c; if (L >= T.nwg) return false; T.map((int)L, u.pm, u.pn); u.seg = 0; return true; }
;     DI bool next(int i, Unit& u) const { const int ti = i / 3; const long L = (long)ti * G + c; if (L >= T.nwg) return false; T.map((int)L, u.pm, u.pn); u.seg = i - 3 * ti; return true; }
;     DI const char* aptr(const Unit& u) const { return A + (size_t)u.pm * ta + (size_t)kofs(u.seg) * 2; }
;     DI const char* bptr(const Unit& u) const { return B + (size_t)u.pn * tb + (size_t)kofs(u.seg) * 2; }
; #define PG8_STAGE(bufoff, gbase, voff) do { _Pragma("unroll") for (int _i = 0; _i < 2; ++_i) \
;         __builtin_amdgcn_global_load_lds((const unsigned*)((const char*)(gbase) + (voff)[_i]), (LAS unsigned*)(lds + (bufoff) + ldsw + _i * 8192), 16, 0, 0); } while (0)
; #define PG8_LDA(dst, b, h) do { _Pragma("unroll") for (int m = 0; m < 4; ++m) _Pragma("unroll") for (int k = 0; k < 2; ++k) dst[m][k] = *(const LAS bf16x8*)(lds + PG8_SA(b, h) + aoff + m * 2048 + k * 1024); } while (0)
; #define PG8_LDB(dst, b, h) do { _Pragma("unroll") for (int n = 0; n < 2; ++n) _Pragma("unroll") for (int k = 0; k < 2; ++k) dst[n][k] = *(const LAS bf16x8*)(lds + PG8_SB(b, h) + boff + n * 2048 + k * 1024); } while (0)
; #define PG8_BAR __builtin_amdgcn_s_barrier()
; template <class Epi, class Sched>
; DI void gemm_phase(LAS unsigned char* lds, const int wv, const int lda, const int ldb, const Sched& S, const Epi& E) {
;     ...
;         const bool has_next = S.next(ui + 1, nxt);
;         const char* nA = has_next ? S.aptr(nxt) : cA; const char* nB = has_next ? S.bptr(nxt) : cB;
;         for (int t = 0; t < nt; t += 2) {
;             const bool last = (t == nt - 2);
;             const char* a1 = cA + (size_t)(t + 1) * kstep;
;             const char* a2 = last ? nA : cA + (size_t)(t + 2) * kstep; const char* b2 = last ? nB : cB + (size_t)(t + 2) * kstep;
;             const char* a3 = a2 + kstep; const char* b3 = b2 + kstep;
;             PG8_LDB(B0, 0, 0); PG8_LDB(B1, 0, 1); PG8_SCHED; PG8_LDA(At, 0, 0); PG8_STAGE(PG8_SA(1, 1), a1 + hstepA, voffA);
;             PG8_WAIT_V(8); PG8_WAIT_L(0); PG8_BAR; PG8_MMA(0, 0, At, B0); PG8_MMA(0, 1, At, B1); PG8_BAR; PG8_SCHED;
;             PG8_LDA(At, 0, 1); PG8_STAGE(PG8_SB(0, 0), b2, voffB); PG8_STAGE(PG8_SB(0, 1), b2 + hstepB, voffB); PG8_STAGE(PG8_SA(0, 0), a2, voffA);
.LBB0_378:
	s_add_u32 s33, s34, 0xfff80080
	s_addc_u32 s36, s35, -1
	s_add_i32 s61, 0, 0x10000
	s_cmp_eq_u32 s23, 28
	s_cselect_b32 s39, s0, s36
	s_cselect_b32 s38, s1, s33
	s_cselect_b32 s37, s5, s19
	s_cselect_b32 s36, s16, s17
	s_add_i32 s33, 0, 0x14000
	v_add_u32_e32 v154, s61, v170
	v_add_u32_e32 v173, s33, v170
	ds_read_b128 v[104:107], v154
	ds_read_b128 v[108:111], v154 offset:1024
	ds_read_b128 v[150:153], v154 offset:2048
	ds_read_b128 v[154:157], v154 offset:3072
	ds_read_b128 v[158:161], v173
	ds_read_b128 v[162:165], v173 offset:1024
	ds_read_b128 v[166:169], v173 offset:2048
	ds_read_b128 v[174:177], v173 offset:3072
	v_lshl_add_u64 v[182:183], s[34:35], 0, v[146:147]
	s_add_i32 m0, s31, 0xc000
	ds_read_b128 v[178:181], v172
	ds_read_b128 v[200:203], v172 offset:1024
	ds_read_b128 v[204:207], v172 offset:2048
	ds_read_b128 v[208:211], v172 offset:3072
	ds_read_b128 v[212:215], v172 offset:4096
	ds_read_b128 v[216:219], v172 offset:5120
	ds_read_b128 v[220:223], v172 offset:6144
	ds_read_b128 v[234:237], v172 offset:7168
	global_load_lds_dwordx4 v[182:183], off
	v_lshl_add_u64 v[182:183], s[34:35], 0, v[148:149]
	s_add_i32 m0, s31, 0xe000
	s_nop 0
	global_load_lds_dwordx4 v[182:183], off
	s_waitcnt vmcnt(8) lgkmcnt(0)
	s_barrier
	v_mfma_f32_16x16x32_bf16 v[132:135], v[104:107], v[178:181], v[132:135]
	v_mfma_f32_16x16x32_bf16 v[128:131], v[150:153], v[178:181], v[128:131]
	v_mfma_f32_16x16x32_bf16 v[124:127], v[104:107], v[204:207], v[124:127]
	v_mfma_f32_16x16x32_bf16 v[120:123], v[150:153], v[204:207], v[120:123]
	v_mfma_f32_16x16x32_bf16 v[116:119], v[104:107], v[212:215], v[116:119]
	v_mfma_f32_16x16x32_bf16 v[112:115], v[150:153], v[212:215], v[112:115]
	v_mfma_f32_16x16x32_bf16 v[100:103], v[104:107], v[220:223], v[100:103]
	v_mfma_f32_16x16x32_bf16 v[96:99], v[150:153], v[220:223], v[96:99]
	v_mfma_f32_16x16x32_bf16 v[132:135], v[108:111], v[200:203], v[132:135]
	v_mfma_f32_16x16x32_bf16 v[128:131], v[154:157], v[200:203], v[128:131]
	v_mfma_f32_16x16x32_bf16 v[124:127], v[108:111], v[208:211], v[124:127]
	v_mfma_f32_16x16x32_bf16 v[120:123], v[154:157], v[208:211], v[120:123]
	v_mfma_f32_16x16x32_bf16 v[116:119], v[108:111], v[216:219], v[116:119]
	v_mfma_f32_16x16x32_bf16 v[112:115], v[154:157], v[216:219], v[112:115]
	v_mfma_f32_16x16x32_bf16 v[100:103], v[108:111], v[234:237], v[100:103]
	v_mfma_f32_16x16x32_bf16 v[96:99], v[154:157], v[234:237], v[96:99]
	v_mfma_f32_16x16x32_bf16 v[60:63], v[158:161], v[178:181], v[60:63]
	v_mfma_f32_16x16x32_bf16 v[56:59], v[166:169], v[178:181], v[56:59]
	v_mfma_f32_16x16x32_bf16 v[52:55], v[158:161], v[204:207], v[52:55]
	v_mfma_f32_16x16x32_bf16 v[48:51], v[166:169], v[204:207], v[48:51]
	v_mfma_f32_16x16x32_bf16 v[44:47], v[158:161], v[212:215], v[44:47]
	v_mfma_f32_16x16x32_bf16 v[40:43], v[166:169], v[212:215], v[40:43]
	v_mfma_f32_16x16x32_bf16 v[36:39], v[158:161], v[220:223], v[36:39]
	v_mfma_f32_16x16x32_bf16 v[32:35], v[166:169], v[220:223], v[32:35]
	v_mfma_f32_16x16x32_bf16 v[60:63], v[162:165], v[200:203], v[60:63]
	v_mfma_f32_16x16x32_bf16 v[56:59], v[174:177], v[200:203], v[56:59]
	v_mfma_f32_16x16x32_bf16 v[52:55], v[162:165], v[208:211], v[52:55]
	v_mfma_f32_16x16x32_bf16 v[48:51], v[174:177], v[208:211], v[48:51]
	v_mfma_f32_16x16x32_bf16 v[44:47], v[162:165], v[216:219], v[44:47]
	v_mfma_f32_16x16x32_bf16 v[40:43], v[174:177], v[216:219], v[40:43]
	v_mfma_f32_16x16x32_bf16 v[36:39], v[162:165], v[234:237], v[36:39]
	v_mfma_f32_16x16x32_bf16 v[32:35], v[174:177], v[234:237], v[32:35]
	s_barrier
	s_add_i32 s61, s61, s47
	v_lshl_add_u64 v[182:183], s[36:37], 0, v[138:139]
	s_mov_b32 m0, s61
	ds_read_b128 v[178:181], v172 offset:16384
	ds_read_b128 v[200:203], v172 offset:17408
	ds_read_b128 v[204:207], v172 offset:18432
	ds_read_b128 v[208:211], v172 offset:19456
	ds_read_b128 v[212:215], v172 offset:20480
	ds_read_b128 v[216:219], v172 offset:21504
	ds_read_b128 v[220:223], v172 offset:22528
	ds_read_b128 v[234:237], v172 offset:23552
	global_load_lds_dwordx4 v[182:183], off
	s_add_i32 m0, s61, 0x2000
	s_add_u32 s62, s36, 0x80000
	v_lshl_add_u64 v[188:189], s[36:37], 0, v[142:143]
	s_addc_u32 s63, s37, 0
	s_add_i32 s33, s33, s47
	global_load_lds_dwordx4 v[188:189], off
	v_lshl_add_u64 v[190:191], s[62:63], 0, v[138:139]
	s_mov_b32 m0, s33
	v_lshl_add_u64 v[196:197], s[38:39], 0, v[140:141]
	global_load_lds_dwordx4 v[190:191], off
	v_lshl_add_u64 v[190:191], s[62:63], 0, v[142:143]
	s_add_i32 m0, s33, 0x2000
	s_nop 0
	global_load_lds_dwordx4 v[190:191], off
	v_lshl_add_u64 v[190:191], s[38:39], 0, v[136:137]
	s_mov_b32 m0, s31
	s_nop 0
	global_load_lds_dwordx4 v[190:191], off
	s_mov_b32 m0, s48
	s_nop 0
	global_load_lds_dwordx4 v[196:197], off
	s_waitcnt vmcnt(8) lgkmcnt(0)
	s_barrier
; #define PG8_STAGE(bufoff, gbase, voff) do { _Pragma("unroll") for (int _i = 0; _i < 2; ++_i) \
;         __builtin_amdgcn_global_load_lds((const unsigned*)((const char*)(gbase) + (voff)[_i]), (LAS unsigned*)(lds + (bufoff) + ldsw + _i * 8192), 16, 0, 0); } while (0)
; #define PG8_LDA(dst, b, h) do { _Pragma("unroll") for (int m = 0; m < 4; ++m) _Pragma("unroll") for (int k = 0; k < 2; ++k) dst[m][k] = *(const LAS bf16x8*)(lds + PG8_SA(b, h) + aoff + m * 2048 + k * 1024); } while (0)
; #define PG8_LDB(dst, b, h) do { _Pragma("unroll") for (int n = 0; n < 2; ++n) _Pragma("unroll") for (int k = 0; k < 2; ++k) dst[n][k] = *(const LAS bf16x8*)(lds + PG8_SB(b, h) + boff + n * 2048 + k * 1024); } while (0)
; #define PG8_MMA(ai, bj, At, Bt) do { __builtin_amdgcn_s_setprio(1); _Pragma("unroll") for (int m = 0; m < 4; ++m) _Pragma("unroll") for (int n = 0; n < 2; ++n) _Pragma("unroll") for (int k = 0; k < 2; ++k) \
;         acc[ai][bj][m][n] = __builtin_amdgcn_mfma_f32_16x16x32_bf16(Bt[n][k], At[m][k], acc[ai][bj][m][n], 0, 0, 0); __builtin_amdgcn_s_setprio(0); } while (0)
; #define PG8_WAIT_V(n) asm volatile("s_waitcnt vmcnt(" #n ")" ::: "memory")
; #define PG8_WAIT_L(n) asm volatile("s_waitcnt lgkmcnt(" #n ")" ::: "memory")
; #define PG8_BAR __builtin_amdgcn_s_barrier()
; #define PG8_SCHED __builtin_amdgcn_sched_barrier(0)
; template <class Epi, class Sched>
; DI void gemm_phase(LAS unsigned char* lds, const int wv, const int lda, const int ldb, const Sched& S, const Epi& E) {
;     ...
;             PG8_WAIT_V(8); PG8_WAIT_L(0); PG8_BAR; PG8_MMA(1, 0, At, B0); PG8_MMA(1, 1, At, B1); PG8_BAR; PG8_SCHED;
;             PG8_LDB(B0, 1, 0); PG8_LDB(B1, 1, 1); PG8_SCHED; PG8_LDA(At, 1, 0); PG8_STAGE(PG8_SA(0, 1), a2 + hstepA, voffA);
;             PG8_WAIT_V(8); PG8_WAIT_L(0); PG8_BAR; PG8_MMA(0, 0, At, B0); PG8_MMA(0, 1, At, B1); PG8_BAR; PG8_SCHED;
	v_mfma_f32_16x16x32_bf16 v[92:95], v[104:107], v[178:181], v[92:95]
	v_mfma_f32_16x16x32_bf16 v[88:91], v[150:153], v[178:181], v[88:91]
	v_mfma_f32_16x16x32_bf16 v[84:87], v[104:107], v[204:207], v[84:87]
	v_mfma_f32_16x16x32_bf16 v[80:83], v[150:153], v[204:207], v[80:83]
	v_mfma_f32_16x16x32_bf16 v[76:79], v[104:107], v[212:215], v[76:79]
	v_mfma_f32_16x16x32_bf16 v[72:75], v[150:153], v[212:215], v[72:75]
	v_mfma_f32_16x16x32_bf16 v[68:71], v[104:107], v[220:223], v[68:71]
	v_mfma_f32_16x16x32_bf16 v[64:67], v[150:153], v[220:223], v[64:67]
	v_mfma_f32_16x16x32_bf16 v[92:95], v[108:111], v[200:203], v[92:95]
	v_mfma_f32_16x16x32_bf16 v[88:91], v[154:157], v[200:203], v[88:91]
	v_mfma_f32_16x16x32_bf16 v[84:87], v[108:111], v[208:211], v[84:87]
	v_mfma_f32_16x16x32_bf16 v[80:83], v[154:157], v[208:211], v[80:83]
	v_mfma_f32_16x16x32_bf16 v[76:79], v[108:111], v[216:219], v[76:79]
	v_mfma_f32_16x16x32_bf16 v[72:75], v[154:157], v[216:219], v[72:75]
	v_mfma_f32_16x16x32_bf16 v[68:71], v[108:111], v[234:237], v[68:71]
	v_mfma_f32_16x16x32_bf16 v[64:67], v[154:157], v[234:237], v[64:67]
	v_mfma_f32_16x16x32_bf16 v[28:31], v[158:161], v[178:181], v[28:31]
	v_mfma_f32_16x16x32_bf16 v[24:27], v[166:169], v[178:181], v[24:27]
	v_mfma_f32_16x16x32_bf16 v[20:23], v[158:161], v[204:207], v[20:23]
	v_mfma_f32_16x16x32_bf16 v[16:19], v[166:169], v[204:207], v[16:19]
	v_mfma_f32_16x16x32_bf16 v[12:15], v[158:161], v[212:215], v[12:15]
	v_mfma_f32_16x16x32_bf16 v[8:11], v[166:169], v[212:215], v[8:11]
	v_mfma_f32_16x16x32_bf16 v[4:7], v[158:161], v[220:223], v[4:7]
	v_mfma_f32_16x16x32_bf16 v[0:3], v[166:169], v[220:223], v[0:3]
	v_mfma_f32_16x16x32_bf16 v[28:31], v[162:165], v[200:203], v[28:31]
	v_mfma_f32_16x16x32_bf16 v[24:27], v[174:177], v[200:203], v[24:27]
	v_mfma_f32_16x16x32_bf16 v[20:23], v[162:165], v[208:211], v[20:23]
	v_mfma_f32_16x16x32_bf16 v[16:19], v[174:177], v[208:211], v[16:19]
	v_mfma_f32_16x16x32_bf16 v[12:15], v[162:165], v[216:219], v[12:15]
	v_mfma_f32_16x16x32_bf16 v[8:11], v[174:177], v[216:219], v[8:11]
	v_mfma_f32_16x16x32_bf16 v[4:7], v[162:165], v[234:237], v[4:7]
	v_mfma_f32_16x16x32_bf16 v[0:3], v[174:177], v[234:237], v[0:3]
	s_barrier
	s_add_i32 s33, 0, 0x18000
	s_add_i32 s61, 0, 0x1c000
	v_add_u32_e32 v154, s33, v170
	v_add_u32_e32 v173, s61, v170
	ds_read_b128 v[104:107], v154
	ds_read_b128 v[108:111], v154 offset:1024
	ds_read_b128 v[150:153], v154 offset:2048
	ds_read_b128 v[154:157], v154 offset:3072
	ds_read_b128 v[158:161], v173
	ds_read_b128 v[162:165], v173 offset:1024
	ds_read_b128 v[166:169], v173 offset:2048
	ds_read_b128 v[174:177], v173 offset:3072
	s_add_u32 s38, s38, 0x80000
	s_addc_u32 s39, s39, 0
	s_mov_b32 m0, s49
	v_lshl_add_u64 v[198:199], s[38:39], 0, v[136:137]
	ds_read_b128 v[178:181], v172 offset:32768
	ds_read_b128 v[200:203], v172 offset:33792
	ds_read_b128 v[204:207], v172 offset:34816
	ds_read_b128 v[208:211], v172 offset:35840
	ds_read_b128 v[212:215], v172 offset:36864
	ds_read_b128 v[216:219], v172 offset:37888
	ds_read_b128 v[220:223], v172 offset:38912
	ds_read_b128 v[234:237], v172 offset:39936
	global_load_lds_dwordx4 v[198:199], off
	v_lshl_add_u64 v[198:199], s[38:39], 0, v[140:141]
	s_mov_b32 m0, s50
	s_nop 0
	global_load_lds_dwordx4 v[198:199], off
	s_waitcnt vmcnt(8) lgkmcnt(0)
	s_barrier
	v_mfma_f32_16x16x32_bf16 v[132:135], v[104:107], v[178:181], v[132:135]
	v_mfma_f32_16x16x32_bf16 v[128:131], v[150:153], v[178:181], v[128:131]
	v_mfma_f32_16x16x32_bf16 v[124:127], v[104:107], v[204:207], v[124:127]
	v_mfma_f32_16x16x32_bf16 v[120:123], v[150:153], v[204:207], v[120:123]
	v_mfma_f32_16x16x32_bf16 v[116:119], v[104:107], v[212:215], v[116:119]
	v_mfma_f32_16x16x32_bf16 v[112:115], v[150:153], v[212:215], v[112:115]
	v_mfma_f32_16x16x32_bf16 v[100:103], v[104:107], v[220:223], v[100:103]
	v_mfma_f32_16x16x32_bf16 v[96:99], v[150:153], v[220:223], v[96:99]
	v_mfma_f32_16x16x32_bf16 v[132:135], v[108:111], v[200:203], v[132:135]
	v_mfma_f32_16x16x32_bf16 v[128:131], v[154:157], v[200:203], v[128:131]
	v_mfma_f32_16x16x32_bf16 v[124:127], v[108:111], v[208:211], v[124:127]
	v_mfma_f32_16x16x32_bf16 v[120:123], v[154:157], v[208:211], v[120:123]
	v_mfma_f32_16x16x32_bf16 v[116:119], v[108:111], v[216:219], v[116:119]
	v_mfma_f32_16x16x32_bf16 v[112:115], v[154:157], v[216:219], v[112:115]
	v_mfma_f32_16x16x32_bf16 v[100:103], v[108:111], v[234:237], v[100:103]
	v_mfma_f32_16x16x32_bf16 v[96:99], v[154:157], v[234:237], v[96:99]
	v_mfma_f32_16x16x32_bf16 v[60:63], v[158:161], v[178:181], v[60:63]
	v_mfma_f32_16x16x32_bf16 v[56:59], v[166:169], v[178:181], v[56:59]
	v_mfma_f32_16x16x32_bf16 v[52:55], v[158:161], v[204:207], v[52:55]
	v_mfma_f32_16x16x32_bf16 v[48:51], v[166:169], v[204:207], v[48:51]
	v_mfma_f32_16x16x32_bf16 v[44:47], v[158:161], v[212:215], v[44:47]
	v_mfma_f32_16x16x32_bf16 v[40:43], v[166:169], v[212:215], v[40:43]
	v_mfma_f32_16x16x32_bf16 v[36:39], v[158:161], v[220:223], v[36:39]
	v_mfma_f32_16x16x32_bf16 v[32:35], v[166:169], v[220:223], v[32:35]
	v_mfma_f32_16x16x32_bf16 v[60:63], v[162:165], v[200:203], v[60:63]
	v_mfma_f32_16x16x32_bf16 v[56:59], v[174:177], v[200:203], v[56:59]
	v_mfma_f32_16x16x32_bf16 v[52:55], v[162:165], v[208:211], v[52:55]
	v_mfma_f32_16x16x32_bf16 v[48:51], v[174:177], v[208:211], v[48:51]
	v_mfma_f32_16x16x32_bf16 v[44:47], v[162:165], v[216:219], v[44:47]
	v_mfma_f32_16x16x32_bf16 v[40:43], v[174:177], v[216:219], v[40:43]
	v_mfma_f32_16x16x32_bf16 v[36:39], v[162:165], v[234:237], v[36:39]
	v_mfma_f32_16x16x32_bf16 v[32:35], v[174:177], v[234:237], v[32:35]
	s_barrier
; #define PG8_STAGE(bufoff, gbase, voff) do { _Pragma("unroll") for (int _i = 0; _i < 2; ++_i) \
;         __builtin_amdgcn_global_load_lds((const unsigned*)((const char*)(gbase) + (voff)[_i]), (LAS unsigned*)(lds + (bufoff) + ldsw + _i * 8192), 16, 0, 0); } while (0)
; #define PG8_LDA(dst, b, h) do { _Pragma("unroll") for (int m = 0; m < 4; ++m) _Pragma("unroll") for (int k = 0; k < 2; ++k) dst[m][k] = *(const LAS bf16x8*)(lds + PG8_SA(b, h) + aoff + m * 2048 + k * 1024); } while (0)
; #define PG8_MMA(ai, bj, At, Bt) do { __builtin_amdgcn_s_setprio(1); _Pragma("unroll") for (int m = 0; m < 4; ++m) _Pragma("unroll") for (int n = 0; n < 2; ++n) _Pragma("unroll") for (int k = 0; k < 2; ++k) \
;         acc[ai][bj][m][n] = __builtin_amdgcn_mfma_f32_16x16x32_bf16(Bt[n][k], At[m][k], acc[ai][bj][m][n], 0, 0, 0); __builtin_amdgcn_s_setprio(0); } while (0)
; #define PG8_WAIT_V(n) asm volatile("s_waitcnt vmcnt(" #n ")" ::: "memory")
; #define PG8_WAIT_L(n) asm volatile("s_waitcnt lgkmcnt(" #n ")" ::: "memory")
; #define PG8_BAR __builtin_amdgcn_s_barrier()
; #define PG8_SCHED __builtin_amdgcn_sched_barrier(0)
; template <class Epi, class Sched>
; DI void gemm_phase(LAS unsigned char* lds, const int wv, const int lda, const int ldb, const Sched& S, const Epi& E) {
;     ...
;             PG8_LDA(At, 1, 1); PG8_STAGE(PG8_SB(1, 0), b3, voffB); PG8_STAGE(PG8_SB(1, 1), b3 + hstepB, voffB); PG8_STAGE(PG8_SA(1, 0), a3, voffA);
;             PG8_WAIT_V(8); PG8_WAIT_L(0); PG8_BAR; PG8_MMA(1, 0, At, B0); PG8_MMA(1, 1, At, B1); PG8_BAR; PG8_SCHED;
;         }
;         if (wr == 0) PG8_BAR;
	s_add_i32 s33, s33, s47
	v_lshl_add_u64 v[182:183], v[182:183], 0, s[28:29]
	s_mov_b32 m0, s33
	ds_read_b128 v[178:181], v172 offset:49152
	ds_read_b128 v[200:203], v172 offset:50176
	ds_read_b128 v[204:207], v172 offset:51200
	ds_read_b128 v[208:211], v172 offset:52224
	ds_read_b128 v[212:215], v172 offset:53248
	ds_read_b128 v[216:219], v172 offset:54272
	ds_read_b128 v[220:223], v172 offset:55296
	ds_read_b128 v[234:237], v172 offset:56320
	global_load_lds_dwordx4 v[182:183], off
	s_add_i32 m0, s33, 0x2000
	s_add_u32 s36, s36, 0x80080
	v_lshl_add_u64 v[182:183], v[188:189], 0, s[28:29]
	s_addc_u32 s37, s37, 0
	s_add_i32 s33, s61, s47
	global_load_lds_dwordx4 v[182:183], off
	v_lshl_add_u64 v[182:183], s[36:37], 0, v[138:139]
	s_mov_b32 m0, s33
	s_nop 0
	global_load_lds_dwordx4 v[182:183], off
	v_lshl_add_u64 v[182:183], s[36:37], 0, v[142:143]
	s_add_i32 m0, s33, 0x2000
	s_nop 0
	global_load_lds_dwordx4 v[182:183], off
	v_lshl_add_u64 v[182:183], v[190:191], 0, s[28:29]
	s_mov_b32 m0, s52
	s_nop 0
	global_load_lds_dwordx4 v[182:183], off
	v_lshl_add_u64 v[182:183], v[196:197], 0, s[28:29]
	s_mov_b32 m0, s53
	s_nop 0
	global_load_lds_dwordx4 v[182:183], off
	s_waitcnt vmcnt(8) lgkmcnt(0)
	s_barrier
	v_mfma_f32_16x16x32_bf16 v[92:95], v[104:107], v[178:181], v[92:95]
	v_mfma_f32_16x16x32_bf16 v[88:91], v[150:153], v[178:181], v[88:91]
	v_mfma_f32_16x16x32_bf16 v[84:87], v[104:107], v[204:207], v[84:87]
	v_mfma_f32_16x16x32_bf16 v[80:83], v[150:153], v[204:207], v[80:83]
	v_mfma_f32_16x16x32_bf16 v[76:79], v[104:107], v[212:215], v[76:79]
	v_mfma_f32_16x16x32_bf16 v[72:75], v[150:153], v[212:215], v[72:75]
	v_mfma_f32_16x16x32_bf16 v[68:71], v[104:107], v[220:223], v[68:71]
	v_mfma_f32_16x16x32_bf16 v[64:67], v[150:153], v[220:223], v[64:67]
	v_mfma_f32_16x16x32_bf16 v[92:95], v[108:111], v[200:203], v[92:95]
	v_mfma_f32_16x16x32_bf16 v[88:91], v[154:157], v[200:203], v[88:91]
	v_mfma_f32_16x16x32_bf16 v[84:87], v[108:111], v[208:211], v[84:87]
	v_mfma_f32_16x16x32_bf16 v[80:83], v[154:157], v[208:211], v[80:83]
	v_mfma_f32_16x16x32_bf16 v[76:79], v[108:111], v[216:219], v[76:79]
	v_mfma_f32_16x16x32_bf16 v[72:75], v[154:157], v[216:219], v[72:75]
	v_mfma_f32_16x16x32_bf16 v[68:71], v[108:111], v[234:237], v[68:71]
	v_mfma_f32_16x16x32_bf16 v[64:67], v[154:157], v[234:237], v[64:67]
	v_mfma_f32_16x16x32_bf16 v[28:31], v[158:161], v[178:181], v[28:31]
	v_mfma_f32_16x16x32_bf16 v[24:27], v[166:169], v[178:181], v[24:27]
	v_mfma_f32_16x16x32_bf16 v[20:23], v[158:161], v[204:207], v[20:23]
	v_mfma_f32_16x16x32_bf16 v[16:19], v[166:169], v[204:207], v[16:19]
	v_mfma_f32_16x16x32_bf16 v[12:15], v[158:161], v[212:215], v[12:15]
	v_mfma_f32_16x16x32_bf16 v[8:11], v[166:169], v[212:215], v[8:11]
	v_mfma_f32_16x16x32_bf16 v[4:7], v[158:161], v[220:223], v[4:7]
	v_mfma_f32_16x16x32_bf16 v[0:3], v[166:169], v[220:223], v[0:3]
	v_mfma_f32_16x16x32_bf16 v[28:31], v[162:165], v[200:203], v[28:31]
	v_mfma_f32_16x16x32_bf16 v[24:27], v[174:177], v[200:203], v[24:27]
	v_mfma_f32_16x16x32_bf16 v[20:23], v[162:165], v[208:211], v[20:23]
	v_mfma_f32_16x16x32_bf16 v[16:19], v[174:177], v[208:211], v[16:19]
	v_mfma_f32_16x16x32_bf16 v[12:15], v[162:165], v[216:219], v[12:15]
	v_mfma_f32_16x16x32_bf16 v[8:11], v[174:177], v[216:219], v[8:11]
	v_mfma_f32_16x16x32_bf16 v[4:7], v[162:165], v[234:237], v[4:7]
	v_mfma_f32_16x16x32_bf16 v[0:3], v[174:177], v[234:237], v[0:3]
	s_barrier
	s_add_i32 s23, s23, 2
	s_add_u32 s34, s34, 0x100
	s_addc_u32 s35, s35, 0
	s_add_u32 s17, s17, 0x100
	s_addc_u32 s19, s19, 0
	s_cmp_gt_u32 s23, 29
	s_cbranch_scc0 .LBB0_378
	s_and_b64 vcc, exec, s[14:15]
	s_cbranch_vccz .LBB0_381
	s_barrier

;     DI bool next(int i, Unit& u) const { const long L = (long)i * G + c; if (L >= T.nwg) return false; T.map((int)L, u.pm, u.pn); u.seg = 0; return true; }
;     DI bool next(int i, Unit& u) const { const int ti = i / 3; const long L = (long)ti * G + c; if (L >= T.nwg) return false; T.map((int)L, u.pm, u.pn); u.seg = i - 3 * ti; return true; }
;     DI const char* aptr(const Unit& u) const { return A + (size_t)u.pm * ta + (size_t)kofs(u.seg) * 2; }
;     DI const char* bptr(const Unit& u) const { return B + (size_t)u.pn * tb + (size_t)kofs(u.seg) * 2; }
; #define PG8_STAGE(bufoff, gbase, voff) do { _Pragma("unroll") for (int _i = 0; _i < 2; ++_i) \
;         __builtin_amdgcn_global_load_lds((const unsigned*)((const char*)(gbase) + (voff)[_i]), (LAS unsigned*)(lds + (bufoff) + ldsw + _i * 8192), 16, 0, 0); } while (0)
; #define PG8_LDA(dst, b, h) do { _Pragma("unroll") for (int m = 0; m < 4; ++m) _Pragma("unroll") for (int k = 0; k < 2; ++k) dst[m][k] = *(const LAS bf16x8*)(lds + PG8_SA(b, h) + aoff + m * 2048 + k * 1024); } while (0)
; #define PG8_LDB(dst, b, h) do { _Pragma("unroll") for (int n = 0; n < 2; ++n) _Pragma("unroll") for (int k = 0; k < 2; ++k) dst[n][k] = *(const LAS bf16x8*)(lds + PG8_SB(b, h) + boff + n * 2048 + k * 1024); } while (0)
; #define PG8_BAR __builtin_amdgcn_s_barrier()
; template <class Epi, class Sched>
; DI void gemm_phase(LAS unsigned char* lds, const int wv, const int lda, const int ldb, const Sched& S, const Epi& E) {
;     ...
;         const bool has_next = S.next(ui + 1, nxt);
;         const char* nA = has_next ? S.aptr(nxt) : cA; const char* nB = has_next ? S.bptr(nxt) : cB;
;         for (int t = 0; t < nt; t += 2) {
;             const bool last = (t == nt - 2);
;             const char* a1 = cA + (size_t)(t + 1) * kstep;
;             const char* a2 = last ? nA : cA + (size_t)(t + 2) * kstep; const char* b2 = last ? nB : cB + (size_t)(t + 2) * kstep;
;             const char* a3 = a2 + kstep; const char* b3 = b2 + kstep;
;             PG8_LDB(B0, 0, 0); PG8_LDB(B1, 0, 1); PG8_SCHED; PG8_LDA(At, 0, 0); PG8_STAGE(PG8_SA(1, 1), a1 + hstepA, voffA);
;             PG8_WAIT_V(8); PG8_WAIT_L(0); PG8_BAR; PG8_MMA(0, 0, At, B0); PG8_MMA(0, 1, At, B1); PG8_BAR; PG8_SCHED;
;             PG8_LDA(At, 0, 1); PG8_STAGE(PG8_SB(0, 0), b2, voffB); PG8_STAGE(PG8_SB(0, 1), b2 + hstepB, voffB); PG8_STAGE(PG8_SA(0, 0), a2, voffA);
.LBB0_1099:
	s_add_u32 s24, s22, 0x100
	s_addc_u32 s25, s23, 0
	s_add_i32 s50, 0, 0x10000
	s_cmp_eq_u32 s49, 8
	s_cselect_b32 s31, s7, s25
	s_cselect_b32 s30, s6, s24
	s_cselect_b32 s27, s19, s1
	s_cselect_b32 s26, s18, s0
	s_add_i32 s51, 0, 0x14000
	v_add_u32_e32 v108, s50, v204
	v_add_u32_e32 v156, s51, v204
	ds_read_b128 v[64:67], v108
	ds_read_b128 v[68:71], v108 offset:1024
	ds_read_b128 v[104:107], v108 offset:2048
	ds_read_b128 v[108:111], v108 offset:3072
	ds_read_b128 v[144:147], v156
	ds_read_b128 v[148:151], v156 offset:1024
	ds_read_b128 v[152:155], v156 offset:2048
	ds_read_b128 v[156:159], v156 offset:3072
	v_lshl_add_u64 v[182:183], s[22:23], 0, v[174:175]
	s_add_i32 m0, s38, 0xc000
	ds_read_b128 v[160:163], v206
	ds_read_b128 v[164:167], v206 offset:1024
	ds_read_b128 v[178:181], v206 offset:2048
	ds_read_b128 v[188:191], v206 offset:3072
	ds_read_b128 v[196:199], v206 offset:4096
	ds_read_b128 v[200:203], v206 offset:5120
	ds_read_b128 v[208:211], v206 offset:6144
	ds_read_b128 v[212:215], v206 offset:7168
	global_load_lds_dwordx4 v[182:183], off
	v_lshl_add_u64 v[182:183], s[22:23], 0, v[176:177]
	s_add_i32 m0, s38, 0xe000
	s_nop 0
	global_load_lds_dwordx4 v[182:183], off
	s_waitcnt vmcnt(8) lgkmcnt(0)
	s_barrier
	v_mfma_f32_16x16x32_bf16 v[140:143], v[64:67], v[160:163], v[140:143]
	v_mfma_f32_16x16x32_bf16 v[136:139], v[104:107], v[160:163], v[136:139]
	v_mfma_f32_16x16x32_bf16 v[132:135], v[64:67], v[178:181], v[132:135]
	v_mfma_f32_16x16x32_bf16 v[128:131], v[104:107], v[178:181], v[128:131]
	v_mfma_f32_16x16x32_bf16 v[124:127], v[64:67], v[196:199], v[124:127]
	v_mfma_f32_16x16x32_bf16 v[120:123], v[104:107], v[196:199], v[120:123]
	v_mfma_f32_16x16x32_bf16 v[116:119], v[64:67], v[208:211], v[116:119]
	v_mfma_f32_16x16x32_bf16 v[112:115], v[104:107], v[208:211], v[112:115]
	v_mfma_f32_16x16x32_bf16 v[140:143], v[68:71], v[164:167], v[140:143]
	v_mfma_f32_16x16x32_bf16 v[136:139], v[108:111], v[164:167], v[136:139]
	v_mfma_f32_16x16x32_bf16 v[132:135], v[68:71], v[188:191], v[132:135]
	v_mfma_f32_16x16x32_bf16 v[128:131], v[108:111], v[188:191], v[128:131]
	v_mfma_f32_16x16x32_bf16 v[124:127], v[68:71], v[200:203], v[124:127]
	v_mfma_f32_16x16x32_bf16 v[120:123], v[108:111], v[200:203], v[120:123]
	v_mfma_f32_16x16x32_bf16 v[116:119], v[68:71], v[212:215], v[116:119]
	v_mfma_f32_16x16x32_bf16 v[112:115], v[108:111], v[212:215], v[112:115]
	v_mfma_f32_16x16x32_bf16 v[100:103], v[144:147], v[160:163], v[100:103]
	v_mfma_f32_16x16x32_bf16 v[96:99], v[152:155], v[160:163], v[96:99]
	v_mfma_f32_16x16x32_bf16 v[92:95], v[144:147], v[178:181], v[92:95]
	v_mfma_f32_16x16x32_bf16 v[88:91], v[152:155], v[178:181], v[88:91]
	v_mfma_f32_16x16x32_bf16 v[84:87], v[144:147], v[196:199], v[84:87]
	v_mfma_f32_16x16x32_bf16 v[80:83], v[152:155], v[196:199], v[80:83]
	v_mfma_f32_16x16x32_bf16 v[76:79], v[144:147], v[208:211], v[76:79]
	v_mfma_f32_16x16x32_bf16 v[72:75], v[152:155], v[208:211], v[72:75]
	v_mfma_f32_16x16x32_bf16 v[100:103], v[148:151], v[164:167], v[100:103]
	v_mfma_f32_16x16x32_bf16 v[96:99], v[156:159], v[164:167], v[96:99]
	v_mfma_f32_16x16x32_bf16 v[92:95], v[148:151], v[188:191], v[92:95]
	v_mfma_f32_16x16x32_bf16 v[88:91], v[156:159], v[188:191], v[88:91]
	v_mfma_f32_16x16x32_bf16 v[84:87], v[148:151], v[200:203], v[84:87]
	v_mfma_f32_16x16x32_bf16 v[80:83], v[156:159], v[200:203], v[80:83]
	v_mfma_f32_16x16x32_bf16 v[76:79], v[148:151], v[212:215], v[76:79]
	v_mfma_f32_16x16x32_bf16 v[72:75], v[156:159], v[212:215], v[72:75]
	s_barrier
	s_add_i32 s22, s50, s36
	v_lshl_add_u64 v[182:183], s[26:27], 0, v[184:185]
	s_mov_b32 m0, s22
	ds_read_b128 v[160:163], v206 offset:16384
	ds_read_b128 v[164:167], v206 offset:17408
	ds_read_b128 v[178:181], v206 offset:18432
	ds_read_b128 v[188:191], v206 offset:19456
	ds_read_b128 v[196:199], v206 offset:20480
	ds_read_b128 v[200:203], v206 offset:21504
	ds_read_b128 v[208:211], v206 offset:22528
	ds_read_b128 v[212:215], v206 offset:23552
	global_load_lds_dwordx4 v[182:183], off
	s_add_i32 m0, s22, 0x2000
	s_add_u32 s22, s26, 0x30000
	v_lshl_add_u64 v[216:217], s[26:27], 0, v[168:169]
	s_addc_u32 s23, s27, 0
	s_add_i32 s50, s51, s36
	global_load_lds_dwordx4 v[216:217], off
	v_lshl_add_u64 v[218:219], s[22:23], 0, v[184:185]
	s_mov_b32 m0, s50
	v_lshl_add_u64 v[220:221], s[30:31], 0, v[170:171]
	global_load_lds_dwordx4 v[218:219], off
	v_lshl_add_u64 v[218:219], s[22:23], 0, v[168:169]
	s_add_i32 m0, s50, 0x2000
	s_nop 0
	global_load_lds_dwordx4 v[218:219], off
	v_lshl_add_u64 v[218:219], s[30:31], 0, v[172:173]
	s_mov_b32 m0, s38
	s_nop 0
	global_load_lds_dwordx4 v[218:219], off
	s_mov_b32 m0, s39
	s_nop 0
	global_load_lds_dwordx4 v[220:221], off
	s_waitcnt vmcnt(8) lgkmcnt(0)
	s_barrier
; #define PG8_STAGE(bufoff, gbase, voff) do { _Pragma("unroll") for (int _i = 0; _i < 2; ++_i) \
;         __builtin_amdgcn_global_load_lds((const unsigned*)((const char*)(gbase) + (voff)[_i]), (LAS unsigned*)(lds + (bufoff) + ldsw + _i * 8192), 16, 0, 0); } while (0)
; #define PG8_LDA(dst, b, h) do { _Pragma("unroll") for (int m = 0; m < 4; ++m) _Pragma("unroll") for (int k = 0; k < 2; ++k) dst[m][k] = *(const LAS bf16x8*)(lds + PG8_SA(b, h) + aoff + m * 2048 + k * 1024); } while (0)
; #define PG8_LDB(dst, b, h) do { _Pragma("unroll") for (int n = 0; n < 2; ++n) _Pragma("unroll") for (int k = 0; k < 2; ++k) dst[n][k] = *(const LAS bf16x8*)(lds + PG8_SB(b, h) + boff + n * 2048 + k * 1024); } while (0)
; #define PG8_MMA(ai, bj, At, Bt) do { __builtin_amdgcn_s_setprio(1); _Pragma("unroll") for (int m = 0; m < 4; ++m) _Pragma("unroll") for (int n = 0; n < 2; ++n) _Pragma("unroll") for (int k = 0; k < 2; ++k) \
;         acc[ai][bj][m][n] = __builtin_amdgcn_mfma_f32_16x16x32_bf16(Bt[n][k], At[m][k], acc[ai][bj][m][n], 0, 0, 0); __builtin_amdgcn_s_setprio(0); } while (0)
; #define PG8_WAIT_V(n) asm volatile("s_waitcnt vmcnt(" #n ")" ::: "memory")
; #define PG8_WAIT_L(n) asm volatile("s_waitcnt lgkmcnt(" #n ")" ::: "memory")
; #define PG8_BAR __builtin_amdgcn_s_barrier()
; #define PG8_SCHED __builtin_amdgcn_sched_barrier(0)
; template <class Epi, class Sched>
; DI void gemm_phase(LAS unsigned char* lds, const int wv, const int lda, const int ldb, const Sched& S, const Epi& E) {
;     ...
;             PG8_WAIT_V(8); PG8_WAIT_L(0); PG8_BAR; PG8_MMA(1, 0, At, B0); PG8_MMA(1, 1, At, B1); PG8_BAR; PG8_SCHED;
;             PG8_LDB(B0, 1, 0); PG8_LDB(B1, 1, 1); PG8_SCHED; PG8_LDA(At, 1, 0); PG8_STAGE(PG8_SA(0, 1), a2 + hstepA, voffA);
;             PG8_WAIT_V(8); PG8_WAIT_L(0); PG8_BAR; PG8_MMA(0, 0, At, B0); PG8_MMA(0, 1, At, B1); PG8_BAR; PG8_SCHED;
	v_mfma_f32_16x16x32_bf16 v[60:63], v[64:67], v[160:163], v[60:63]
	v_mfma_f32_16x16x32_bf16 v[56:59], v[104:107], v[160:163], v[56:59]
	v_mfma_f32_16x16x32_bf16 v[52:55], v[64:67], v[178:181], v[52:55]
	v_mfma_f32_16x16x32_bf16 v[48:51], v[104:107], v[178:181], v[48:51]
	v_mfma_f32_16x16x32_bf16 v[44:47], v[64:67], v[196:199], v[44:47]
	v_mfma_f32_16x16x32_bf16 v[40:43], v[104:107], v[196:199], v[40:43]
	v_mfma_f32_16x16x32_bf16 v[36:39], v[64:67], v[208:211], v[36:39]
	v_mfma_f32_16x16x32_bf16 v[32:35], v[104:107], v[208:211], v[32:35]
	v_mfma_f32_16x16x32_bf16 v[60:63], v[68:71], v[164:167], v[60:63]
	v_mfma_f32_16x16x32_bf16 v[56:59], v[108:111], v[164:167], v[56:59]
	v_mfma_f32_16x16x32_bf16 v[52:55], v[68:71], v[188:191], v[52:55]
	v_mfma_f32_16x16x32_bf16 v[48:51], v[108:111], v[188:191], v[48:51]
	v_mfma_f32_16x16x32_bf16 v[44:47], v[68:71], v[200:203], v[44:47]
	v_mfma_f32_16x16x32_bf16 v[40:43], v[108:111], v[200:203], v[40:43]
	v_mfma_f32_16x16x32_bf16 v[36:39], v[68:71], v[212:215], v[36:39]
	v_mfma_f32_16x16x32_bf16 v[32:35], v[108:111], v[212:215], v[32:35]
	v_mfma_f32_16x16x32_bf16 v[28:31], v[144:147], v[160:163], v[28:31]
	v_mfma_f32_16x16x32_bf16 v[24:27], v[152:155], v[160:163], v[24:27]
	v_mfma_f32_16x16x32_bf16 v[20:23], v[144:147], v[178:181], v[20:23]
	v_mfma_f32_16x16x32_bf16 v[16:19], v[152:155], v[178:181], v[16:19]
	v_mfma_f32_16x16x32_bf16 v[12:15], v[144:147], v[196:199], v[12:15]
	v_mfma_f32_16x16x32_bf16 v[8:11], v[152:155], v[196:199], v[8:11]
	v_mfma_f32_16x16x32_bf16 v[4:7], v[144:147], v[208:211], v[4:7]
	v_mfma_f32_16x16x32_bf16 v[0:3], v[152:155], v[208:211], v[0:3]
	v_mfma_f32_16x16x32_bf16 v[28:31], v[148:151], v[164:167], v[28:31]
	v_mfma_f32_16x16x32_bf16 v[24:27], v[156:159], v[164:167], v[24:27]
	v_mfma_f32_16x16x32_bf16 v[20:23], v[148:151], v[188:191], v[20:23]
	v_mfma_f32_16x16x32_bf16 v[16:19], v[156:159], v[188:191], v[16:19]
	v_mfma_f32_16x16x32_bf16 v[12:15], v[148:151], v[200:203], v[12:15]
	v_mfma_f32_16x16x32_bf16 v[8:11], v[156:159], v[200:203], v[8:11]
	v_mfma_f32_16x16x32_bf16 v[4:7], v[148:151], v[212:215], v[4:7]
	v_mfma_f32_16x16x32_bf16 v[0:3], v[156:159], v[212:215], v[0:3]
	s_barrier
	s_add_i32 s50, 0, 0x18000
	s_add_i32 s51, 0, 0x1c000
	v_add_u32_e32 v108, s50, v204
	v_add_u32_e32 v156, s51, v204
	ds_read_b128 v[64:67], v108
	ds_read_b128 v[68:71], v108 offset:1024
	ds_read_b128 v[104:107], v108 offset:2048
	ds_read_b128 v[108:111], v108 offset:3072
	ds_read_b128 v[144:147], v156
	ds_read_b128 v[148:151], v156 offset:1024
	ds_read_b128 v[152:155], v156 offset:2048
	ds_read_b128 v[156:159], v156 offset:3072
	s_add_u32 s22, s30, 0x30000
	s_addc_u32 s23, s31, 0
	s_mov_b32 m0, s40
	v_lshl_add_u64 v[222:223], s[22:23], 0, v[172:173]
	ds_read_b128 v[160:163], v206 offset:32768
	ds_read_b128 v[164:167], v206 offset:33792
	ds_read_b128 v[178:181], v206 offset:34816
	ds_read_b128 v[188:191], v206 offset:35840
	ds_read_b128 v[196:199], v206 offset:36864
	ds_read_b128 v[200:203], v206 offset:37888
	ds_read_b128 v[208:211], v206 offset:38912
	ds_read_b128 v[212:215], v206 offset:39936
	global_load_lds_dwordx4 v[222:223], off
	v_lshl_add_u64 v[222:223], s[22:23], 0, v[170:171]
	s_mov_b32 m0, s41
	s_nop 0
	global_load_lds_dwordx4 v[222:223], off
	s_waitcnt vmcnt(8) lgkmcnt(0)
	s_barrier
	v_mfma_f32_16x16x32_bf16 v[140:143], v[64:67], v[160:163], v[140:143]
	v_mfma_f32_16x16x32_bf16 v[136:139], v[104:107], v[160:163], v[136:139]
	v_mfma_f32_16x16x32_bf16 v[132:135], v[64:67], v[178:181], v[132:135]
	v_mfma_f32_16x16x32_bf16 v[128:131], v[104:107], v[178:181], v[128:131]
	v_mfma_f32_16x16x32_bf16 v[124:127], v[64:67], v[196:199], v[124:127]
	v_mfma_f32_16x16x32_bf16 v[120:123], v[104:107], v[196:199], v[120:123]
	v_mfma_f32_16x16x32_bf16 v[116:119], v[64:67], v[208:211], v[116:119]
	v_mfma_f32_16x16x32_bf16 v[112:115], v[104:107], v[208:211], v[112:115]
	v_mfma_f32_16x16x32_bf16 v[140:143], v[68:71], v[164:167], v[140:143]
	v_mfma_f32_16x16x32_bf16 v[136:139], v[108:111], v[164:167], v[136:139]
	v_mfma_f32_16x16x32_bf16 v[132:135], v[68:71], v[188:191], v[132:135]
	v_mfma_f32_16x16x32_bf16 v[128:131], v[108:111], v[188:191], v[128:131]
	v_mfma_f32_16x16x32_bf16 v[124:127], v[68:71], v[200:203], v[124:127]
	v_mfma_f32_16x16x32_bf16 v[120:123], v[108:111], v[200:203], v[120:123]
	v_mfma_f32_16x16x32_bf16 v[116:119], v[68:71], v[212:215], v[116:119]
	v_mfma_f32_16x16x32_bf16 v[112:115], v[108:111], v[212:215], v[112:115]
	v_mfma_f32_16x16x32_bf16 v[100:103], v[144:147], v[160:163], v[100:103]
	v_mfma_f32_16x16x32_bf16 v[96:99], v[152:155], v[160:163], v[96:99]
	v_mfma_f32_16x16x32_bf16 v[92:95], v[144:147], v[178:181], v[92:95]
	v_mfma_f32_16x16x32_bf16 v[88:91], v[152:155], v[178:181], v[88:91]
	v_mfma_f32_16x16x32_bf16 v[84:87], v[144:147], v[196:199], v[84:87]
	v_mfma_f32_16x16x32_bf16 v[80:83], v[152:155], v[196:199], v[80:83]
	v_mfma_f32_16x16x32_bf16 v[76:79], v[144:147], v[208:211], v[76:79]
	v_mfma_f32_16x16x32_bf16 v[72:75], v[152:155], v[208:211], v[72:75]
	v_mfma_f32_16x16x32_bf16 v[100:103], v[148:151], v[164:167], v[100:103]
	v_mfma_f32_16x16x32_bf16 v[96:99], v[156:159], v[164:167], v[96:99]
	v_mfma_f32_16x16x32_bf16 v[92:95], v[148:151], v[188:191], v[92:95]
	v_mfma_f32_16x16x32_bf16 v[88:91], v[156:159], v[188:191], v[88:91]
	v_mfma_f32_16x16x32_bf16 v[84:87], v[148:151], v[200:203], v[84:87]
	v_mfma_f32_16x16x32_bf16 v[80:83], v[156:159], v[200:203], v[80:83]
	v_mfma_f32_16x16x32_bf16 v[76:79], v[148:151], v[212:215], v[76:79]
	v_mfma_f32_16x16x32_bf16 v[72:75], v[156:159], v[212:215], v[72:75]
	s_barrier
; #define PG8_STAGE(bufoff, gbase, voff) do { _Pragma("unroll") for (int _i = 0; _i < 2; ++_i) \
;         __builtin_amdgcn_global_load_lds((const unsigned*)((const char*)(gbase) + (voff)[_i]), (LAS unsigned*)(lds + (bufoff) + ldsw + _i * 8192), 16, 0, 0); } while (0)
; #define PG8_LDA(dst, b, h) do { _Pragma("unroll") for (int m = 0; m < 4; ++m) _Pragma("unroll") for (int k = 0; k < 2; ++k) dst[m][k] = *(const LAS bf16x8*)(lds + PG8_SA(b, h) + aoff + m * 2048 + k * 1024); } while (0)
; #define PG8_MMA(ai, bj, At, Bt) do { __builtin_amdgcn_s_setprio(1); _Pragma("unroll") for (int m = 0; m < 4; ++m) _Pragma("unroll") for (int n = 0; n < 2; ++n) _Pragma("unroll") for (int k = 0; k < 2; ++k) \
;         acc[ai][bj][m][n] = __builtin_amdgcn_mfma_f32_16x16x32_bf16(Bt[n][k], At[m][k], acc[ai][bj][m][n], 0, 0, 0); __builtin_amdgcn_s_setprio(0); } while (0)
; #define PG8_WAIT_V(n) asm volatile("s_waitcnt vmcnt(" #n ")" ::: "memory")
; #define PG8_WAIT_L(n) asm volatile("s_waitcnt lgkmcnt(" #n ")" ::: "memory")
; #define PG8_BAR __builtin_amdgcn_s_barrier()
; #define PG8_SCHED __builtin_amdgcn_sched_barrier(0)
; template <class Epi, class Sched>
; DI void gemm_phase(LAS unsigned char* lds, const int wv, const int lda, const int ldb, const Sched& S, const Epi& E) {
;     ...
;             PG8_LDA(At, 1, 1); PG8_STAGE(PG8_SB(1, 0), b3, voffB); PG8_STAGE(PG8_SB(1, 1), b3 + hstepB, voffB); PG8_STAGE(PG8_SA(1, 0), a3, voffA);
;             PG8_WAIT_V(8); PG8_WAIT_L(0); PG8_BAR; PG8_MMA(1, 0, At, B0); PG8_MMA(1, 1, At, B1); PG8_BAR; PG8_SCHED;
;         }
;         if (wr == 0) PG8_BAR;
	s_add_i32 s22, s50, s36
	v_lshl_add_u64 v[182:183], v[182:183], 0, s[28:29]
	s_mov_b32 m0, s22
	ds_read_b128 v[160:163], v206 offset:49152
	ds_read_b128 v[164:167], v206 offset:50176
	ds_read_b128 v[178:181], v206 offset:51200
	ds_read_b128 v[188:191], v206 offset:52224
	ds_read_b128 v[196:199], v206 offset:53248
	ds_read_b128 v[200:203], v206 offset:54272
	ds_read_b128 v[208:211], v206 offset:55296
	ds_read_b128 v[212:215], v206 offset:56320
	global_load_lds_dwordx4 v[182:183], off
	s_add_i32 m0, s22, 0x2000
	s_add_u32 s22, s26, 0x30080
	v_lshl_add_u64 v[182:183], v[216:217], 0, s[28:29]
	s_addc_u32 s23, s27, 0
	s_add_i32 s26, s51, s36
	global_load_lds_dwordx4 v[182:183], off
	v_lshl_add_u64 v[182:183], s[22:23], 0, v[184:185]
	s_mov_b32 m0, s26
	s_nop 0
	global_load_lds_dwordx4 v[182:183], off
	v_lshl_add_u64 v[182:183], s[22:23], 0, v[168:169]
	s_add_i32 m0, s26, 0x2000
	s_nop 0
	global_load_lds_dwordx4 v[182:183], off
	v_lshl_add_u64 v[182:183], v[218:219], 0, s[28:29]
	s_mov_b32 m0, s20
	s_nop 0
	global_load_lds_dwordx4 v[182:183], off
	v_lshl_add_u64 v[182:183], v[220:221], 0, s[28:29]
	s_mov_b32 m0, s42
	s_nop 0
	global_load_lds_dwordx4 v[182:183], off
	s_waitcnt vmcnt(8) lgkmcnt(0)
	s_barrier
	v_mfma_f32_16x16x32_bf16 v[60:63], v[64:67], v[160:163], v[60:63]
	v_mfma_f32_16x16x32_bf16 v[56:59], v[104:107], v[160:163], v[56:59]
	v_mfma_f32_16x16x32_bf16 v[52:55], v[64:67], v[178:181], v[52:55]
	v_mfma_f32_16x16x32_bf16 v[48:51], v[104:107], v[178:181], v[48:51]
	v_mfma_f32_16x16x32_bf16 v[44:47], v[64:67], v[196:199], v[44:47]
	v_mfma_f32_16x16x32_bf16 v[40:43], v[104:107], v[196:199], v[40:43]
	v_mfma_f32_16x16x32_bf16 v[36:39], v[64:67], v[208:211], v[36:39]
	v_mfma_f32_16x16x32_bf16 v[32:35], v[104:107], v[208:211], v[32:35]
	v_mfma_f32_16x16x32_bf16 v[60:63], v[68:71], v[164:167], v[60:63]
	v_mfma_f32_16x16x32_bf16 v[56:59], v[108:111], v[164:167], v[56:59]
	v_mfma_f32_16x16x32_bf16 v[52:55], v[68:71], v[188:191], v[52:55]
	v_mfma_f32_16x16x32_bf16 v[48:51], v[108:111], v[188:191], v[48:51]
	v_mfma_f32_16x16x32_bf16 v[44:47], v[68:71], v[200:203], v[44:47]
	v_mfma_f32_16x16x32_bf16 v[40:43], v[108:111], v[200:203], v[40:43]
	v_mfma_f32_16x16x32_bf16 v[36:39], v[68:71], v[212:215], v[36:39]
	v_mfma_f32_16x16x32_bf16 v[32:35], v[108:111], v[212:215], v[32:35]
	v_mfma_f32_16x16x32_bf16 v[28:31], v[144:147], v[160:163], v[28:31]
	v_mfma_f32_16x16x32_bf16 v[24:27], v[152:155], v[160:163], v[24:27]
	v_mfma_f32_16x16x32_bf16 v[20:23], v[144:147], v[178:181], v[20:23]
	v_mfma_f32_16x16x32_bf16 v[16:19], v[152:155], v[178:181], v[16:19]
	v_mfma_f32_16x16x32_bf16 v[12:15], v[144:147], v[196:199], v[12:15]
	v_mfma_f32_16x16x32_bf16 v[8:11], v[152:155], v[196:199], v[8:11]
	v_mfma_f32_16x16x32_bf16 v[4:7], v[144:147], v[208:211], v[4:7]
	v_mfma_f32_16x16x32_bf16 v[0:3], v[152:155], v[208:211], v[0:3]
	v_mfma_f32_16x16x32_bf16 v[28:31], v[148:151], v[164:167], v[28:31]
	v_mfma_f32_16x16x32_bf16 v[24:27], v[156:159], v[164:167], v[24:27]
	v_mfma_f32_16x16x32_bf16 v[20:23], v[148:151], v[188:191], v[20:23]
	v_mfma_f32_16x16x32_bf16 v[16:19], v[156:159], v[188:191], v[16:19]
	v_mfma_f32_16x16x32_bf16 v[12:15], v[148:151], v[200:203], v[12:15]
	v_mfma_f32_16x16x32_bf16 v[8:11], v[156:159], v[200:203], v[8:11]
	v_mfma_f32_16x16x32_bf16 v[4:7], v[148:151], v[212:215], v[4:7]
	v_mfma_f32_16x16x32_bf16 v[0:3], v[156:159], v[212:215], v[0:3]
	s_barrier
	s_add_i32 s49, s49, 2
	s_add_u32 s0, s0, 0x100
	s_addc_u32 s1, s1, 0
	s_cmp_gt_u32 s49, 9
	s_mov_b64 s[22:23], s[24:25]
	s_cbranch_scc0 .LBB0_1099
	s_and_b64 vcc, exec, s[14:15]
	s_cbranch_vccz .LBB0_1102
	s_barrier

;     DI bool next(int i, Unit& u) const { const long L = (long)i * G + c; if (L >= T.nwg) return false; T.map((int)L, u.pm, u.pn); u.seg = 0; return true; }
;     DI bool next(int i, Unit& u) const { const int ti = i / 3; const long L = (long)ti * G + c; if (L >= T.nwg) return false; T.map((int)L, u.pm, u.pn); u.seg = i - 3 * ti; return true; }
;     DI const char* aptr(const Unit& u) const { return A + (size_t)u.pm * ta + (size_t)kofs(u.seg) * 2; }
;     DI const char* bptr(const Unit& u) const { return B + (size_t)u.pn * tb + (size_t)kofs(u.seg) * 2; }
; #define PG8_STAGE(bufoff, gbase, voff) do { _Pragma("unroll") for (int _i = 0; _i < 2; ++_i) \
;         __builtin_amdgcn_global_load_lds((const unsigned*)((const char*)(gbase) + (voff)[_i]), (LAS unsigned*)(lds + (bufoff) + ldsw + _i * 8192), 16, 0, 0); } while (0)
; #define PG8_LDA(dst, b, h) do { _Pragma("unroll") for (int m = 0; m < 4; ++m) _Pragma("unroll") for (int k = 0; k < 2; ++k) dst[m][k] = *(const LAS bf16x8*)(lds + PG8_SA(b, h) + aoff + m * 2048 + k * 1024); } while (0)
; #define PG8_LDB(dst, b, h) do { _Pragma("unroll") for (int n = 0; n < 2; ++n) _Pragma("unroll") for (int k = 0; k < 2; ++k) dst[n][k] = *(const LAS bf16x8*)(lds + PG8_SB(b, h) + boff + n * 2048 + k * 1024); } while (0)
; #define PG8_BAR __builtin_amdgcn_s_barrier()
; template <class Epi, class Sched>
; DI void gemm_phase(LAS unsigned char* lds, const int wv, const int lda, const int ldb, const Sched& S, const Epi& E) {
;     ...
;         const bool has_next = S.next(ui + 1, nxt);
;         const char* nA = has_next ? S.aptr(nxt) : cA; const char* nB = has_next ? S.bptr(nxt) : cB;
;         for (int t = 0; t < nt; t += 2) {
;             const bool last = (t == nt - 2);
;             const char* a1 = cA + (size_t)(t + 1) * kstep;
;             const char* a2 = last ? nA : cA + (size_t)(t + 2) * kstep; const char* b2 = last ? nB : cB + (size_t)(t + 2) * kstep;
;             const char* a3 = a2 + kstep; const char* b3 = b2 + kstep;
;             PG8_LDB(B0, 0, 0); PG8_LDB(B1, 0, 1); PG8_SCHED; PG8_LDA(At, 0, 0); PG8_STAGE(PG8_SA(1, 1), a1 + hstepA, voffA);
;             PG8_WAIT_V(8); PG8_WAIT_L(0); PG8_BAR; PG8_MMA(0, 0, At, B0); PG8_MMA(0, 1, At, B1); PG8_BAR; PG8_SCHED;
;             PG8_LDA(At, 0, 1); PG8_STAGE(PG8_SB(0, 0), b2, voffB); PG8_STAGE(PG8_SB(0, 1), b2 + hstepB, voffB); PG8_STAGE(PG8_SA(0, 0), a2, voffA);
.LBB0_1185:
	s_add_i32 s31, s19, 2
	s_add_u32 s34, s6, 0xfff80080
	s_addc_u32 s35, s7, -1
	s_add_i32 s40, 0, 0x10000
	s_cmp_eq_u32 s0, s19
	s_cselect_b32 s37, s23, s35
	s_cselect_b32 s36, s22, s34
	s_cselect_b32 s35, s25, s15
	s_cselect_b32 s34, s24, s1
	s_add_i32 s19, 0, 0x14000
	v_add_u32_e32 v140, s40, v233
	v_add_u32_e32 v156, s19, v233
	ds_read_b128 v[128:131], v140
	ds_read_b128 v[132:135], v140 offset:1024
	ds_read_b128 v[136:139], v140 offset:2048
	ds_read_b128 v[140:143], v140 offset:3072
	ds_read_b128 v[144:147], v156
	ds_read_b128 v[148:151], v156 offset:1024
	ds_read_b128 v[152:155], v156 offset:2048
	ds_read_b128 v[156:159], v156 offset:3072
	v_lshl_add_u64 v[210:211], s[6:7], 0, v[206:207]
	s_add_i32 m0, s45, 0xc000
	ds_read_b128 v[160:163], v235
	ds_read_b128 v[164:167], v235 offset:1024
	ds_read_b128 v[168:171], v235 offset:2048
	ds_read_b128 v[172:175], v235 offset:3072
	ds_read_b128 v[176:179], v235 offset:4096
	ds_read_b128 v[180:183], v235 offset:5120
	ds_read_b128 v[188:191], v235 offset:6144
	ds_read_b128 v[196:199], v235 offset:7168
	global_load_lds_dwordx4 v[210:211], off
	v_lshl_add_u64 v[210:211], s[6:7], 0, v[208:209]
	s_add_i32 m0, s45, 0xe000
	s_nop 0
	global_load_lds_dwordx4 v[210:211], off
	s_waitcnt vmcnt(8) lgkmcnt(0)
	s_barrier
	v_mfma_f32_16x16x32_bf16 v[124:127], v[128:131], v[160:163], v[124:127]
	v_mfma_f32_16x16x32_bf16 v[120:123], v[136:139], v[160:163], v[120:123]
	v_mfma_f32_16x16x32_bf16 v[116:119], v[128:131], v[168:171], v[116:119]
	v_mfma_f32_16x16x32_bf16 v[112:115], v[136:139], v[168:171], v[112:115]
	v_mfma_f32_16x16x32_bf16 v[108:111], v[128:131], v[176:179], v[108:111]
	v_mfma_f32_16x16x32_bf16 v[104:107], v[136:139], v[176:179], v[104:107]
	v_mfma_f32_16x16x32_bf16 v[100:103], v[128:131], v[188:191], v[100:103]
	v_mfma_f32_16x16x32_bf16 v[96:99], v[136:139], v[188:191], v[96:99]
	v_mfma_f32_16x16x32_bf16 v[124:127], v[132:135], v[164:167], v[124:127]
	v_mfma_f32_16x16x32_bf16 v[120:123], v[140:143], v[164:167], v[120:123]
	v_mfma_f32_16x16x32_bf16 v[116:119], v[132:135], v[172:175], v[116:119]
	v_mfma_f32_16x16x32_bf16 v[112:115], v[140:143], v[172:175], v[112:115]
	v_mfma_f32_16x16x32_bf16 v[108:111], v[132:135], v[180:183], v[108:111]
	v_mfma_f32_16x16x32_bf16 v[104:107], v[140:143], v[180:183], v[104:107]
	v_mfma_f32_16x16x32_bf16 v[100:103], v[132:135], v[196:199], v[100:103]
	v_mfma_f32_16x16x32_bf16 v[96:99], v[140:143], v[196:199], v[96:99]
	v_mfma_f32_16x16x32_bf16 v[92:95], v[144:147], v[160:163], v[92:95]
	v_mfma_f32_16x16x32_bf16 v[88:91], v[152:155], v[160:163], v[88:91]
	v_mfma_f32_16x16x32_bf16 v[84:87], v[144:147], v[168:171], v[84:87]
	v_mfma_f32_16x16x32_bf16 v[80:83], v[152:155], v[168:171], v[80:83]
	v_mfma_f32_16x16x32_bf16 v[76:79], v[144:147], v[176:179], v[76:79]
	v_mfma_f32_16x16x32_bf16 v[72:75], v[152:155], v[176:179], v[72:75]
	v_mfma_f32_16x16x32_bf16 v[68:71], v[144:147], v[188:191], v[68:71]
	v_mfma_f32_16x16x32_bf16 v[64:67], v[152:155], v[188:191], v[64:67]
	v_mfma_f32_16x16x32_bf16 v[92:95], v[148:151], v[164:167], v[92:95]
	v_mfma_f32_16x16x32_bf16 v[88:91], v[156:159], v[164:167], v[88:91]
	v_mfma_f32_16x16x32_bf16 v[84:87], v[148:151], v[172:175], v[84:87]
	v_mfma_f32_16x16x32_bf16 v[80:83], v[156:159], v[172:175], v[80:83]
	v_mfma_f32_16x16x32_bf16 v[76:79], v[148:151], v[180:183], v[76:79]
	v_mfma_f32_16x16x32_bf16 v[72:75], v[156:159], v[180:183], v[72:75]
	v_mfma_f32_16x16x32_bf16 v[68:71], v[148:151], v[196:199], v[68:71]
	v_mfma_f32_16x16x32_bf16 v[64:67], v[156:159], v[196:199], v[64:67]
	s_barrier
	s_add_i32 s40, s40, s44
	v_lshl_add_u64 v[210:211], s[34:35], 0, v[184:185]
	s_mov_b32 m0, s40
	ds_read_b128 v[160:163], v235 offset:16384
	ds_read_b128 v[164:167], v235 offset:17408
	ds_read_b128 v[168:171], v235 offset:18432
	ds_read_b128 v[172:175], v235 offset:19456
	ds_read_b128 v[176:179], v235 offset:20480
	ds_read_b128 v[180:183], v235 offset:21504
	ds_read_b128 v[188:191], v235 offset:22528
	ds_read_b128 v[196:199], v235 offset:23552
	global_load_lds_dwordx4 v[210:211], off
	s_add_i32 m0, s40, 0x2000
	s_add_u32 s40, s34, 0x80000
	v_lshl_add_u64 v[212:213], s[34:35], 0, v[204:205]
	s_addc_u32 s41, s35, 0
	s_add_i32 s19, s19, s44
	global_load_lds_dwordx4 v[212:213], off
	v_lshl_add_u64 v[214:215], s[40:41], 0, v[184:185]
	s_mov_b32 m0, s19
	v_lshl_add_u64 v[216:217], s[36:37], 0, v[202:203]
	global_load_lds_dwordx4 v[214:215], off
	v_lshl_add_u64 v[214:215], s[40:41], 0, v[204:205]
	s_add_i32 m0, s19, 0x2000
	s_nop 0
	global_load_lds_dwordx4 v[214:215], off
	v_lshl_add_u64 v[214:215], s[36:37], 0, v[200:201]
	s_mov_b32 m0, s45
	s_nop 0
	global_load_lds_dwordx4 v[214:215], off
	s_mov_b32 m0, s46
	s_nop 0
	global_load_lds_dwordx4 v[216:217], off
	s_waitcnt vmcnt(8) lgkmcnt(0)
	s_barrier
; #define PG8_STAGE(bufoff, gbase, voff) do { _Pragma("unroll") for (int _i = 0; _i < 2; ++_i) \
;         __builtin_amdgcn_global_load_lds((const unsigned*)((const char*)(gbase) + (voff)[_i]), (LAS unsigned*)(lds + (bufoff) + ldsw + _i * 8192), 16, 0, 0); } while (0)
; #define PG8_LDA(dst, b, h) do { _Pragma("unroll") for (int m = 0; m < 4; ++m) _Pragma("unroll") for (int k = 0; k < 2; ++k) dst[m][k] = *(const LAS bf16x8*)(lds + PG8_SA(b, h) + aoff + m * 2048 + k * 1024); } while (0)
; #define PG8_LDB(dst, b, h) do { _Pragma("unroll") for (int n = 0; n < 2; ++n) _Pragma("unroll") for (int k = 0; k < 2; ++k) dst[n][k] = *(const LAS bf16x8*)(lds + PG8_SB(b, h) + boff + n * 2048 + k * 1024); } while (0)
; #define PG8_MMA(ai, bj, At, Bt) do { __builtin_amdgcn_s_setprio(1); _Pragma("unroll") for (int m = 0; m < 4; ++m) _Pragma("unroll") for (int n = 0; n < 2; ++n) _Pragma("unroll") for (int k = 0; k < 2; ++k) \
;         acc[ai][bj][m][n] = __builtin_amdgcn_mfma_f32_16x16x32_bf16(Bt[n][k], At[m][k], acc[ai][bj][m][n], 0, 0, 0); __builtin_amdgcn_s_setprio(0); } while (0)
; #define PG8_WAIT_V(n) asm volatile("s_waitcnt vmcnt(" #n ")" ::: "memory")
; #define PG8_WAIT_L(n) asm volatile("s_waitcnt lgkmcnt(" #n ")" ::: "memory")
; #define PG8_BAR __builtin_amdgcn_s_barrier()
; #define PG8_SCHED __builtin_amdgcn_sched_barrier(0)
; template <class Epi, class Sched>
; DI void gemm_phase(LAS unsigned char* lds, const int wv, const int lda, const int ldb, const Sched& S, const Epi& E) {
;     ...
;             PG8_WAIT_V(8); PG8_WAIT_L(0); PG8_BAR; PG8_MMA(1, 0, At, B0); PG8_MMA(1, 1, At, B1); PG8_BAR; PG8_SCHED;
;             PG8_LDB(B0, 1, 0); PG8_LDB(B1, 1, 1); PG8_SCHED; PG8_LDA(At, 1, 0); PG8_STAGE(PG8_SA(0, 1), a2 + hstepA, voffA);
;             PG8_WAIT_V(8); PG8_WAIT_L(0); PG8_BAR; PG8_MMA(0, 0, At, B0); PG8_MMA(0, 1, At, B1); PG8_BAR; PG8_SCHED;
	v_mfma_f32_16x16x32_bf16 v[60:63], v[128:131], v[160:163], v[60:63]
	v_mfma_f32_16x16x32_bf16 v[56:59], v[136:139], v[160:163], v[56:59]
	v_mfma_f32_16x16x32_bf16 v[52:55], v[128:131], v[168:171], v[52:55]
	v_mfma_f32_16x16x32_bf16 v[48:51], v[136:139], v[168:171], v[48:51]
	v_mfma_f32_16x16x32_bf16 v[44:47], v[128:131], v[176:179], v[44:47]
	v_mfma_f32_16x16x32_bf16 v[40:43], v[136:139], v[176:179], v[40:43]
	v_mfma_f32_16x16x32_bf16 v[36:39], v[128:131], v[188:191], v[36:39]
	v_mfma_f32_16x16x32_bf16 v[32:35], v[136:139], v[188:191], v[32:35]
	v_mfma_f32_16x16x32_bf16 v[60:63], v[132:135], v[164:167], v[60:63]
	v_mfma_f32_16x16x32_bf16 v[56:59], v[140:143], v[164:167], v[56:59]
	v_mfma_f32_16x16x32_bf16 v[52:55], v[132:135], v[172:175], v[52:55]
	v_mfma_f32_16x16x32_bf16 v[48:51], v[140:143], v[172:175], v[48:51]
	v_mfma_f32_16x16x32_bf16 v[44:47], v[132:135], v[180:183], v[44:47]
	v_mfma_f32_16x16x32_bf16 v[40:43], v[140:143], v[180:183], v[40:43]
	v_mfma_f32_16x16x32_bf16 v[36:39], v[132:135], v[196:199], v[36:39]
	v_mfma_f32_16x16x32_bf16 v[32:35], v[140:143], v[196:199], v[32:35]
	v_mfma_f32_16x16x32_bf16 v[28:31], v[144:147], v[160:163], v[28:31]
	v_mfma_f32_16x16x32_bf16 v[24:27], v[152:155], v[160:163], v[24:27]
	v_mfma_f32_16x16x32_bf16 v[20:23], v[144:147], v[168:171], v[20:23]
	v_mfma_f32_16x16x32_bf16 v[16:19], v[152:155], v[168:171], v[16:19]
	v_mfma_f32_16x16x32_bf16 v[12:15], v[144:147], v[176:179], v[12:15]
	v_mfma_f32_16x16x32_bf16 v[8:11], v[152:155], v[176:179], v[8:11]
	v_mfma_f32_16x16x32_bf16 v[4:7], v[144:147], v[188:191], v[4:7]
	v_mfma_f32_16x16x32_bf16 v[0:3], v[152:155], v[188:191], v[0:3]
	v_mfma_f32_16x16x32_bf16 v[28:31], v[148:151], v[164:167], v[28:31]
	v_mfma_f32_16x16x32_bf16 v[24:27], v[156:159], v[164:167], v[24:27]
	v_mfma_f32_16x16x32_bf16 v[20:23], v[148:151], v[172:175], v[20:23]
	v_mfma_f32_16x16x32_bf16 v[16:19], v[156:159], v[172:175], v[16:19]
	v_mfma_f32_16x16x32_bf16 v[12:15], v[148:151], v[180:183], v[12:15]
	v_mfma_f32_16x16x32_bf16 v[8:11], v[156:159], v[180:183], v[8:11]
	v_mfma_f32_16x16x32_bf16 v[4:7], v[148:151], v[196:199], v[4:7]
	v_mfma_f32_16x16x32_bf16 v[0:3], v[156:159], v[196:199], v[0:3]
	s_barrier
	s_add_i32 s19, 0, 0x18000
	s_add_i32 s40, 0, 0x1c000
	v_add_u32_e32 v140, s19, v233
	v_add_u32_e32 v156, s40, v233
	ds_read_b128 v[128:131], v140
	ds_read_b128 v[132:135], v140 offset:1024
	ds_read_b128 v[136:139], v140 offset:2048
	ds_read_b128 v[140:143], v140 offset:3072
	ds_read_b128 v[144:147], v156
	ds_read_b128 v[148:151], v156 offset:1024
	ds_read_b128 v[152:155], v156 offset:2048
	ds_read_b128 v[156:159], v156 offset:3072
	s_add_u32 s36, s36, 0x80000
	s_addc_u32 s37, s37, 0
	s_mov_b32 m0, s47
	v_lshl_add_u64 v[218:219], s[36:37], 0, v[200:201]
	ds_read_b128 v[160:163], v235 offset:32768
	ds_read_b128 v[164:167], v235 offset:33792
	ds_read_b128 v[168:171], v235 offset:34816
	ds_read_b128 v[172:175], v235 offset:35840
	ds_read_b128 v[176:179], v235 offset:36864
	ds_read_b128 v[180:183], v235 offset:37888
	ds_read_b128 v[188:191], v235 offset:38912
	ds_read_b128 v[196:199], v235 offset:39936
	global_load_lds_dwordx4 v[218:219], off
	v_lshl_add_u64 v[218:219], s[36:37], 0, v[202:203]
	s_mov_b32 m0, s48
	s_nop 0
	global_load_lds_dwordx4 v[218:219], off
	s_waitcnt vmcnt(8) lgkmcnt(0)
	s_barrier
	v_mfma_f32_16x16x32_bf16 v[124:127], v[128:131], v[160:163], v[124:127]
	v_mfma_f32_16x16x32_bf16 v[120:123], v[136:139], v[160:163], v[120:123]
	v_mfma_f32_16x16x32_bf16 v[116:119], v[128:131], v[168:171], v[116:119]
	v_mfma_f32_16x16x32_bf16 v[112:115], v[136:139], v[168:171], v[112:115]
	v_mfma_f32_16x16x32_bf16 v[108:111], v[128:131], v[176:179], v[108:111]
	v_mfma_f32_16x16x32_bf16 v[104:107], v[136:139], v[176:179], v[104:107]
	v_mfma_f32_16x16x32_bf16 v[100:103], v[128:131], v[188:191], v[100:103]
	v_mfma_f32_16x16x32_bf16 v[96:99], v[136:139], v[188:191], v[96:99]
	v_mfma_f32_16x16x32_bf16 v[124:127], v[132:135], v[164:167], v[124:127]
	v_mfma_f32_16x16x32_bf16 v[120:123], v[140:143], v[164:167], v[120:123]
	v_mfma_f32_16x16x32_bf16 v[116:119], v[132:135], v[172:175], v[116:119]
	v_mfma_f32_16x16x32_bf16 v[112:115], v[140:143], v[172:175], v[112:115]
	v_mfma_f32_16x16x32_bf16 v[108:111], v[132:135], v[180:183], v[108:111]
	v_mfma_f32_16x16x32_bf16 v[104:107], v[140:143], v[180:183], v[104:107]
	v_mfma_f32_16x16x32_bf16 v[100:103], v[132:135], v[196:199], v[100:103]
	v_mfma_f32_16x16x32_bf16 v[96:99], v[140:143], v[196:199], v[96:99]
	v_mfma_f32_16x16x32_bf16 v[92:95], v[144:147], v[160:163], v[92:95]
	v_mfma_f32_16x16x32_bf16 v[88:91], v[152:155], v[160:163], v[88:91]
	v_mfma_f32_16x16x32_bf16 v[84:87], v[144:147], v[168:171], v[84:87]
	v_mfma_f32_16x16x32_bf16 v[80:83], v[152:155], v[168:171], v[80:83]
	v_mfma_f32_16x16x32_bf16 v[76:79], v[144:147], v[176:179], v[76:79]
	v_mfma_f32_16x16x32_bf16 v[72:75], v[152:155], v[176:179], v[72:75]
	v_mfma_f32_16x16x32_bf16 v[68:71], v[144:147], v[188:191], v[68:71]
	v_mfma_f32_16x16x32_bf16 v[64:67], v[152:155], v[188:191], v[64:67]
	v_mfma_f32_16x16x32_bf16 v[92:95], v[148:151], v[164:167], v[92:95]
	v_mfma_f32_16x16x32_bf16 v[88:91], v[156:159], v[164:167], v[88:91]
	v_mfma_f32_16x16x32_bf16 v[84:87], v[148:151], v[172:175], v[84:87]
	v_mfma_f32_16x16x32_bf16 v[80:83], v[156:159], v[172:175], v[80:83]
	v_mfma_f32_16x16x32_bf16 v[76:79], v[148:151], v[180:183], v[76:79]
	v_mfma_f32_16x16x32_bf16 v[72:75], v[156:159], v[180:183], v[72:75]
	v_mfma_f32_16x16x32_bf16 v[68:71], v[148:151], v[196:199], v[68:71]
	v_mfma_f32_16x16x32_bf16 v[64:67], v[156:159], v[196:199], v[64:67]
	s_barrier
; #define PG8_STAGE(bufoff, gbase, voff) do { _Pragma("unroll") for (int _i = 0; _i < 2; ++_i) \
;         __builtin_amdgcn_global_load_lds((const unsigned*)((const char*)(gbase) + (voff)[_i]), (LAS unsigned*)(lds + (bufoff) + ldsw + _i * 8192), 16, 0, 0); } while (0)
; #define PG8_LDA(dst, b, h) do { _Pragma("unroll") for (int m = 0; m < 4; ++m) _Pragma("unroll") for (int k = 0; k < 2; ++k) dst[m][k] = *(const LAS bf16x8*)(lds + PG8_SA(b, h) + aoff + m * 2048 + k * 1024); } while (0)
; #define PG8_MMA(ai, bj, At, Bt) do { __builtin_amdgcn_s_setprio(1); _Pragma("unroll") for (int m = 0; m < 4; ++m) _Pragma("unroll") for (int n = 0; n < 2; ++n) _Pragma("unroll") for (int k = 0; k < 2; ++k) \
;         acc[ai][bj][m][n] = __builtin_amdgcn_mfma_f32_16x16x32_bf16(Bt[n][k], At[m][k], acc[ai][bj][m][n], 0, 0, 0); __builtin_amdgcn_s_setprio(0); } while (0)
; #define PG8_WAIT_V(n) asm volatile("s_waitcnt vmcnt(" #n ")" ::: "memory")
; #define PG8_WAIT_L(n) asm volatile("s_waitcnt lgkmcnt(" #n ")" ::: "memory")
; #define PG8_BAR __builtin_amdgcn_s_barrier()
; #define PG8_SCHED __builtin_amdgcn_sched_barrier(0)
; template <class Epi, class Sched>
; DI void gemm_phase(LAS unsigned char* lds, const int wv, const int lda, const int ldb, const Sched& S, const Epi& E) {
;     ...
;             PG8_LDA(At, 1, 1); PG8_STAGE(PG8_SB(1, 0), b3, voffB); PG8_STAGE(PG8_SB(1, 1), b3 + hstepB, voffB); PG8_STAGE(PG8_SA(1, 0), a3, voffA);
;             PG8_WAIT_V(8); PG8_WAIT_L(0); PG8_BAR; PG8_MMA(1, 0, At, B0); PG8_MMA(1, 1, At, B1); PG8_BAR; PG8_SCHED;
;         }
;         if (wr == 0) PG8_BAR;
	s_add_i32 s19, s19, s44
	v_lshl_add_u64 v[210:211], v[210:211], 0, s[28:29]
	s_mov_b32 m0, s19
	ds_read_b128 v[160:163], v235 offset:49152
	ds_read_b128 v[164:167], v235 offset:50176
	ds_read_b128 v[168:171], v235 offset:51200
	ds_read_b128 v[172:175], v235 offset:52224
	ds_read_b128 v[176:179], v235 offset:53248
	ds_read_b128 v[180:183], v235 offset:54272
	ds_read_b128 v[188:191], v235 offset:55296
	ds_read_b128 v[196:199], v235 offset:56320
	global_load_lds_dwordx4 v[210:211], off
	s_add_i32 m0, s19, 0x2000
	s_add_u32 s34, s34, 0x80080
	v_lshl_add_u64 v[210:211], v[212:213], 0, s[28:29]
	s_addc_u32 s35, s35, 0
	s_add_i32 s19, s40, s44
	global_load_lds_dwordx4 v[210:211], off
	v_lshl_add_u64 v[210:211], s[34:35], 0, v[184:185]
	s_mov_b32 m0, s19
	s_nop 0
	global_load_lds_dwordx4 v[210:211], off
	v_lshl_add_u64 v[210:211], s[34:35], 0, v[204:205]
	s_add_i32 m0, s19, 0x2000
	s_nop 0
	global_load_lds_dwordx4 v[210:211], off
	v_lshl_add_u64 v[210:211], v[214:215], 0, s[28:29]
	s_mov_b32 m0, s49
	s_nop 0
	global_load_lds_dwordx4 v[210:211], off
	v_lshl_add_u64 v[210:211], v[216:217], 0, s[28:29]
	s_mov_b32 m0, s50
	s_nop 0
	global_load_lds_dwordx4 v[210:211], off
	s_waitcnt vmcnt(8) lgkmcnt(0)
	s_barrier
	v_mfma_f32_16x16x32_bf16 v[60:63], v[128:131], v[160:163], v[60:63]
	v_mfma_f32_16x16x32_bf16 v[56:59], v[136:139], v[160:163], v[56:59]
	v_mfma_f32_16x16x32_bf16 v[52:55], v[128:131], v[168:171], v[52:55]
	v_mfma_f32_16x16x32_bf16 v[48:51], v[136:139], v[168:171], v[48:51]
	v_mfma_f32_16x16x32_bf16 v[44:47], v[128:131], v[176:179], v[44:47]
	v_mfma_f32_16x16x32_bf16 v[40:43], v[136:139], v[176:179], v[40:43]
	v_mfma_f32_16x16x32_bf16 v[36:39], v[128:131], v[188:191], v[36:39]
	v_mfma_f32_16x16x32_bf16 v[32:35], v[136:139], v[188:191], v[32:35]
	v_mfma_f32_16x16x32_bf16 v[60:63], v[132:135], v[164:167], v[60:63]
	v_mfma_f32_16x16x32_bf16 v[56:59], v[140:143], v[164:167], v[56:59]
	v_mfma_f32_16x16x32_bf16 v[52:55], v[132:135], v[172:175], v[52:55]
	v_mfma_f32_16x16x32_bf16 v[48:51], v[140:143], v[172:175], v[48:51]
	v_mfma_f32_16x16x32_bf16 v[44:47], v[132:135], v[180:183], v[44:47]
	v_mfma_f32_16x16x32_bf16 v[40:43], v[140:143], v[180:183], v[40:43]
	v_mfma_f32_16x16x32_bf16 v[36:39], v[132:135], v[196:199], v[36:39]
	v_mfma_f32_16x16x32_bf16 v[32:35], v[140:143], v[196:199], v[32:35]
	v_mfma_f32_16x16x32_bf16 v[28:31], v[144:147], v[160:163], v[28:31]
	v_mfma_f32_16x16x32_bf16 v[24:27], v[152:155], v[160:163], v[24:27]
	v_mfma_f32_16x16x32_bf16 v[20:23], v[144:147], v[168:171], v[20:23]
	v_mfma_f32_16x16x32_bf16 v[16:19], v[152:155], v[168:171], v[16:19]
	v_mfma_f32_16x16x32_bf16 v[12:15], v[144:147], v[176:179], v[12:15]
	v_mfma_f32_16x16x32_bf16 v[8:11], v[152:155], v[176:179], v[8:11]
	v_mfma_f32_16x16x32_bf16 v[4:7], v[144:147], v[188:191], v[4:7]
	v_mfma_f32_16x16x32_bf16 v[0:3], v[152:155], v[188:191], v[0:3]
	v_mfma_f32_16x16x32_bf16 v[28:31], v[148:151], v[164:167], v[28:31]
	v_mfma_f32_16x16x32_bf16 v[24:27], v[156:159], v[164:167], v[24:27]
	v_mfma_f32_16x16x32_bf16 v[20:23], v[148:151], v[172:175], v[20:23]
	v_mfma_f32_16x16x32_bf16 v[16:19], v[156:159], v[172:175], v[16:19]
	v_mfma_f32_16x16x32_bf16 v[12:15], v[148:151], v[180:183], v[12:15]
	v_mfma_f32_16x16x32_bf16 v[8:11], v[156:159], v[180:183], v[8:11]
	v_mfma_f32_16x16x32_bf16 v[4:7], v[148:151], v[196:199], v[4:7]
	v_mfma_f32_16x16x32_bf16 v[0:3], v[156:159], v[196:199], v[0:3]
	s_barrier
	s_add_u32 s6, s6, 0x100
	s_addc_u32 s7, s7, 0
	s_add_u32 s1, s1, 0x100
	s_addc_u32 s15, s15, 0
	s_cmp_ge_u32 s31, s27
	s_mov_b32 s19, s31
	s_cbranch_scc0 .LBB0_1185
	s_and_b64 vcc, exec, s[12:13]
	s_cbranch_vccz .LBB0_1188
	s_barrier

;     DI bool next(int i, Unit& u) const { const long L = (long)i * G + c; if (L >= T.nwg) return false; T.map((int)L, u.pm, u.pn); u.seg = 0; return true; }
;     DI bool next(int i, Unit& u) const { const int ti = i / 3; const long L = (long)ti * G + c; if (L >= T.nwg) return false; T.map((int)L, u.pm, u.pn); u.seg = i - 3 * ti; return true; }
;     DI const char* aptr(const Unit& u) const { return A + (size_t)u.pm * ta + (size_t)kofs(u.seg) * 2; }
;     DI const char* bptr(const Unit& u) const { return B + (size_t)u.pn * tb + (size_t)kofs(u.seg) * 2; }
; #define PG8_STAGE(bufoff, gbase, voff) do { _Pragma("unroll") for (int _i = 0; _i < 2; ++_i) \
;         __builtin_amdgcn_global_load_lds((const unsigned*)((const char*)(gbase) + (voff)[_i]), (LAS unsigned*)(lds + (bufoff) + ldsw + _i * 8192), 16, 0, 0); } while (0)
; #define PG8_LDA(dst, b, h) do { _Pragma("unroll") for (int m = 0; m < 4; ++m) _Pragma("unroll") for (int k = 0; k < 2; ++k) dst[m][k] = *(const LAS bf16x8*)(lds + PG8_SA(b, h) + aoff + m * 2048 + k * 1024); } while (0)
; #define PG8_LDB(dst, b, h) do { _Pragma("unroll") for (int n = 0; n < 2; ++n) _Pragma("unroll") for (int k = 0; k < 2; ++k) dst[n][k] = *(const LAS bf16x8*)(lds + PG8_SB(b, h) + boff + n * 2048 + k * 1024); } while (0)
; #define PG8_BAR __builtin_amdgcn_s_barrier()
; template <class Epi, class Sched>
; DI void gemm_phase(LAS unsigned char* lds, const int wv, const int lda, const int ldb, const Sched& S, const Epi& E) {
;     ...
;         const bool has_next = S.next(ui + 1, nxt);
;         const char* nA = has_next ? S.aptr(nxt) : cA; const char* nB = has_next ? S.bptr(nxt) : cB;
;         for (int t = 0; t < nt; t += 2) {
;             const bool last = (t == nt - 2);
;             const char* a1 = cA + (size_t)(t + 1) * kstep;
;             const char* a2 = last ? nA : cA + (size_t)(t + 2) * kstep; const char* b2 = last ? nB : cB + (size_t)(t + 2) * kstep;
;             const char* a3 = a2 + kstep; const char* b3 = b2 + kstep;
;             PG8_LDB(B0, 0, 0); PG8_LDB(B1, 0, 1); PG8_SCHED; PG8_LDA(At, 0, 0); PG8_STAGE(PG8_SA(1, 1), a1 + hstepA, voffA);
;             PG8_WAIT_V(8); PG8_WAIT_L(0); PG8_BAR; PG8_MMA(0, 0, At, B0); PG8_MMA(0, 1, At, B1); PG8_BAR; PG8_SCHED;
;             PG8_LDA(At, 0, 1); PG8_STAGE(PG8_SB(0, 0), b2, voffB); PG8_STAGE(PG8_SB(0, 1), b2 + hstepB, voffB); PG8_STAGE(PG8_SA(0, 0), a2, voffA);
.LBB0_1299:
	s_add_u32 s34, s30, 0xfff80080
	s_addc_u32 s35, s31, -1
	s_add_i32 s54, 0, 0x10000
	s_cmp_eq_u32 s53, 28
	s_cselect_b32 s37, s0, s35
	s_cselect_b32 s36, s1, s34
	s_cselect_b32 s35, s11, s52
	s_cselect_b32 s34, s15, s19
	s_add_i32 s56, 0, 0x14000
	v_add_u32_e32 v150, s54, v155
	v_add_u32_e32 v172, s56, v155
	ds_read_b128 v[128:131], v150
	ds_read_b128 v[142:145], v150 offset:1024
	ds_read_b128 v[146:149], v150 offset:2048
	ds_read_b128 v[150:153], v150 offset:3072
	ds_read_b128 v[160:163], v172
	ds_read_b128 v[164:167], v172 offset:1024
	ds_read_b128 v[168:171], v172 offset:2048
	ds_read_b128 v[172:175], v172 offset:3072
	v_lshl_add_u64 v[216:217], s[30:31], 0, v[138:139]
	s_add_i32 m0, s27, 0xc000
	ds_read_b128 v[176:179], v159
	ds_read_b128 v[180:183], v159 offset:1024
	ds_read_b128 v[188:191], v159 offset:2048
	ds_read_b128 v[196:199], v159 offset:3072
	ds_read_b128 v[200:203], v159 offset:4096
	ds_read_b128 v[204:207], v159 offset:5120
	ds_read_b128 v[208:211], v159 offset:6144
	ds_read_b128 v[212:215], v159 offset:7168
	global_load_lds_dwordx4 v[216:217], off
	v_lshl_add_u64 v[216:217], s[30:31], 0, v[140:141]
	s_add_i32 m0, s27, 0xe000
	s_nop 0
	global_load_lds_dwordx4 v[216:217], off
	s_waitcnt vmcnt(8) lgkmcnt(0)
	s_barrier
	v_mfma_f32_16x16x32_bf16 v[124:127], v[128:131], v[176:179], v[124:127]
	v_mfma_f32_16x16x32_bf16 v[120:123], v[146:149], v[176:179], v[120:123]
	v_mfma_f32_16x16x32_bf16 v[108:111], v[128:131], v[188:191], v[108:111]
	v_mfma_f32_16x16x32_bf16 v[104:107], v[146:149], v[188:191], v[104:107]
	v_mfma_f32_16x16x32_bf16 v[96:99], v[128:131], v[200:203], v[96:99]
	v_mfma_f32_16x16x32_bf16 v[88:91], v[146:149], v[200:203], v[88:91]
	v_mfma_f32_16x16x32_bf16 v[80:83], v[128:131], v[208:211], v[80:83]
	v_mfma_f32_16x16x32_bf16 v[72:75], v[146:149], v[208:211], v[72:75]
	v_mfma_f32_16x16x32_bf16 v[124:127], v[142:145], v[180:183], v[124:127]
	v_mfma_f32_16x16x32_bf16 v[120:123], v[150:153], v[180:183], v[120:123]
	v_mfma_f32_16x16x32_bf16 v[108:111], v[142:145], v[196:199], v[108:111]
	v_mfma_f32_16x16x32_bf16 v[104:107], v[150:153], v[196:199], v[104:107]
	v_mfma_f32_16x16x32_bf16 v[96:99], v[142:145], v[204:207], v[96:99]
	v_mfma_f32_16x16x32_bf16 v[88:91], v[150:153], v[204:207], v[88:91]
	v_mfma_f32_16x16x32_bf16 v[80:83], v[142:145], v[212:215], v[80:83]
	v_mfma_f32_16x16x32_bf16 v[72:75], v[150:153], v[212:215], v[72:75]
	v_mfma_f32_16x16x32_bf16 v[116:119], v[160:163], v[176:179], v[116:119]
	v_mfma_f32_16x16x32_bf16 v[112:115], v[168:171], v[176:179], v[112:115]
	v_mfma_f32_16x16x32_bf16 v[100:103], v[160:163], v[188:191], v[100:103]
	v_mfma_f32_16x16x32_bf16 v[92:95], v[168:171], v[188:191], v[92:95]
	v_mfma_f32_16x16x32_bf16 v[84:87], v[160:163], v[200:203], v[84:87]
	v_mfma_f32_16x16x32_bf16 v[76:79], v[168:171], v[200:203], v[76:79]
	v_mfma_f32_16x16x32_bf16 v[68:71], v[160:163], v[208:211], v[68:71]
	v_mfma_f32_16x16x32_bf16 v[64:67], v[168:171], v[208:211], v[64:67]
	v_mfma_f32_16x16x32_bf16 v[116:119], v[164:167], v[180:183], v[116:119]
	v_mfma_f32_16x16x32_bf16 v[112:115], v[172:175], v[180:183], v[112:115]
	v_mfma_f32_16x16x32_bf16 v[100:103], v[164:167], v[196:199], v[100:103]
	v_mfma_f32_16x16x32_bf16 v[92:95], v[172:175], v[196:199], v[92:95]
	v_mfma_f32_16x16x32_bf16 v[84:87], v[164:167], v[204:207], v[84:87]
	v_mfma_f32_16x16x32_bf16 v[76:79], v[172:175], v[204:207], v[76:79]
	v_mfma_f32_16x16x32_bf16 v[68:71], v[164:167], v[212:215], v[68:71]
	v_mfma_f32_16x16x32_bf16 v[64:67], v[172:175], v[212:215], v[64:67]
	s_barrier
	s_add_i32 s54, s54, s41
	v_lshl_add_u64 v[216:217], s[34:35], 0, v[184:185]
	s_mov_b32 m0, s54
	ds_read_b128 v[176:179], v159 offset:16384
	ds_read_b128 v[180:183], v159 offset:17408
	ds_read_b128 v[188:191], v159 offset:18432
	ds_read_b128 v[196:199], v159 offset:19456
	ds_read_b128 v[200:203], v159 offset:20480
	ds_read_b128 v[204:207], v159 offset:21504
	ds_read_b128 v[208:211], v159 offset:22528
	ds_read_b128 v[212:215], v159 offset:23552
	global_load_lds_dwordx4 v[216:217], off
	s_add_i32 m0, s54, 0x2000
	s_add_u32 s54, s34, 0x80000
	v_lshl_add_u64 v[218:219], s[34:35], 0, v[136:137]
	s_addc_u32 s55, s35, 0
	s_add_i32 s56, s56, s41
	global_load_lds_dwordx4 v[218:219], off
	v_lshl_add_u64 v[220:221], s[54:55], 0, v[184:185]
	s_mov_b32 m0, s56
	v_lshl_add_u64 v[222:223], s[36:37], 0, v[134:135]
	global_load_lds_dwordx4 v[220:221], off
	v_lshl_add_u64 v[220:221], s[54:55], 0, v[136:137]
	s_add_i32 m0, s56, 0x2000
	s_nop 0
	global_load_lds_dwordx4 v[220:221], off
	v_lshl_add_u64 v[220:221], s[36:37], 0, v[132:133]
	s_mov_b32 m0, s27
	s_nop 0
	global_load_lds_dwordx4 v[220:221], off
	s_mov_b32 m0, s42
	s_nop 0
	global_load_lds_dwordx4 v[222:223], off
	s_waitcnt vmcnt(8) lgkmcnt(0)
	s_barrier
; #define PG8_STAGE(bufoff, gbase, voff) do { _Pragma("unroll") for (int _i = 0; _i < 2; ++_i) \
;         __builtin_amdgcn_global_load_lds((const unsigned*)((const char*)(gbase) + (voff)[_i]), (LAS unsigned*)(lds + (bufoff) + ldsw + _i * 8192), 16, 0, 0); } while (0)
; #define PG8_LDA(dst, b, h) do { _Pragma("unroll") for (int m = 0; m < 4; ++m) _Pragma("unroll") for (int k = 0; k < 2; ++k) dst[m][k] = *(const LAS bf16x8*)(lds + PG8_SA(b, h) + aoff + m * 2048 + k * 1024); } while (0)
; #define PG8_LDB(dst, b, h) do { _Pragma("unroll") for (int n = 0; n < 2; ++n) _Pragma("unroll") for (int k = 0; k < 2; ++k) dst[n][k] = *(const LAS bf16x8*)(lds + PG8_SB(b, h) + boff + n * 2048 + k * 1024); } while (0)
; #define PG8_MMA(ai, bj, At, Bt) do { __builtin_amdgcn_s_setprio(1); _Pragma("unroll") for (int m = 0; m < 4; ++m) _Pragma("unroll") for (int n = 0; n < 2; ++n) _Pragma("unroll") for (int k = 0; k < 2; ++k) \
;         acc[ai][bj][m][n] = __builtin_amdgcn_mfma_f32_16x16x32_bf16(Bt[n][k], At[m][k], acc[ai][bj][m][n], 0, 0, 0); __builtin_amdgcn_s_setprio(0); } while (0)
; #define PG8_WAIT_V(n) asm volatile("s_waitcnt vmcnt(" #n ")" ::: "memory")
; #define PG8_WAIT_L(n) asm volatile("s_waitcnt lgkmcnt(" #n ")" ::: "memory")
; #define PG8_BAR __builtin_amdgcn_s_barrier()
; #define PG8_SCHED __builtin_amdgcn_sched_barrier(0)
; template <class Epi, class Sched>
; DI void gemm_phase(LAS unsigned char* lds, const int wv, const int lda, const int ldb, const Sched& S, const Epi& E) {
;     ...
;             PG8_WAIT_V(8); PG8_WAIT_L(0); PG8_BAR; PG8_MMA(1, 0, At, B0); PG8_MMA(1, 1, At, B1); PG8_BAR; PG8_SCHED;
;             PG8_LDB(B0, 1, 0); PG8_LDB(B1, 1, 1); PG8_SCHED; PG8_LDA(At, 1, 0); PG8_STAGE(PG8_SA(0, 1), a2 + hstepA, voffA);
;             PG8_WAIT_V(8); PG8_WAIT_L(0); PG8_BAR; PG8_MMA(0, 0, At, B0); PG8_MMA(0, 1, At, B1); PG8_BAR; PG8_SCHED;
	v_mfma_f32_16x16x32_bf16 v[60:63], v[128:131], v[176:179], v[60:63]
	v_mfma_f32_16x16x32_bf16 v[56:59], v[146:149], v[176:179], v[56:59]
	v_mfma_f32_16x16x32_bf16 v[48:51], v[128:131], v[188:191], v[48:51]
	v_mfma_f32_16x16x32_bf16 v[40:43], v[146:149], v[188:191], v[40:43]
	v_mfma_f32_16x16x32_bf16 v[32:35], v[128:131], v[200:203], v[32:35]
	v_mfma_f32_16x16x32_bf16 v[24:27], v[146:149], v[200:203], v[24:27]
	v_mfma_f32_16x16x32_bf16 v[16:19], v[128:131], v[208:211], v[16:19]
	v_mfma_f32_16x16x32_bf16 v[8:11], v[146:149], v[208:211], v[8:11]
	v_mfma_f32_16x16x32_bf16 v[60:63], v[142:145], v[180:183], v[60:63]
	v_mfma_f32_16x16x32_bf16 v[56:59], v[150:153], v[180:183], v[56:59]
	v_mfma_f32_16x16x32_bf16 v[48:51], v[142:145], v[196:199], v[48:51]
	v_mfma_f32_16x16x32_bf16 v[40:43], v[150:153], v[196:199], v[40:43]
	v_mfma_f32_16x16x32_bf16 v[32:35], v[142:145], v[204:207], v[32:35]
	v_mfma_f32_16x16x32_bf16 v[24:27], v[150:153], v[204:207], v[24:27]
	v_mfma_f32_16x16x32_bf16 v[16:19], v[142:145], v[212:215], v[16:19]
	v_mfma_f32_16x16x32_bf16 v[8:11], v[150:153], v[212:215], v[8:11]
	v_mfma_f32_16x16x32_bf16 v[52:55], v[160:163], v[176:179], v[52:55]
	v_mfma_f32_16x16x32_bf16 v[44:47], v[168:171], v[176:179], v[44:47]
	v_mfma_f32_16x16x32_bf16 v[36:39], v[160:163], v[188:191], v[36:39]
	v_mfma_f32_16x16x32_bf16 v[28:31], v[168:171], v[188:191], v[28:31]
	v_mfma_f32_16x16x32_bf16 v[20:23], v[160:163], v[200:203], v[20:23]
	v_mfma_f32_16x16x32_bf16 v[12:15], v[168:171], v[200:203], v[12:15]
	v_mfma_f32_16x16x32_bf16 v[4:7], v[160:163], v[208:211], v[4:7]
	v_mfma_f32_16x16x32_bf16 v[0:3], v[168:171], v[208:211], v[0:3]
	v_mfma_f32_16x16x32_bf16 v[52:55], v[164:167], v[180:183], v[52:55]
	v_mfma_f32_16x16x32_bf16 v[44:47], v[172:175], v[180:183], v[44:47]
	v_mfma_f32_16x16x32_bf16 v[36:39], v[164:167], v[196:199], v[36:39]
	v_mfma_f32_16x16x32_bf16 v[28:31], v[172:175], v[196:199], v[28:31]
	v_mfma_f32_16x16x32_bf16 v[20:23], v[164:167], v[204:207], v[20:23]
	v_mfma_f32_16x16x32_bf16 v[12:15], v[172:175], v[204:207], v[12:15]
	v_mfma_f32_16x16x32_bf16 v[4:7], v[164:167], v[212:215], v[4:7]
	v_mfma_f32_16x16x32_bf16 v[0:3], v[172:175], v[212:215], v[0:3]
	s_barrier
	s_add_i32 s54, 0, 0x18000
	s_add_i32 s55, 0, 0x1c000
	v_add_u32_e32 v150, s54, v155
	v_add_u32_e32 v172, s55, v155
	ds_read_b128 v[128:131], v150
	ds_read_b128 v[142:145], v150 offset:1024
	ds_read_b128 v[146:149], v150 offset:2048
	ds_read_b128 v[150:153], v150 offset:3072
	ds_read_b128 v[160:163], v172
	ds_read_b128 v[164:167], v172 offset:1024
	ds_read_b128 v[168:171], v172 offset:2048
	ds_read_b128 v[172:175], v172 offset:3072
	s_add_u32 s36, s36, 0x80000
	s_addc_u32 s37, s37, 0
	s_mov_b32 m0, s43
	v_lshl_add_u64 v[234:235], s[36:37], 0, v[132:133]
	ds_read_b128 v[176:179], v159 offset:32768
	ds_read_b128 v[180:183], v159 offset:33792
	ds_read_b128 v[188:191], v159 offset:34816
	ds_read_b128 v[196:199], v159 offset:35840
	ds_read_b128 v[200:203], v159 offset:36864
	ds_read_b128 v[204:207], v159 offset:37888
	ds_read_b128 v[208:211], v159 offset:38912
	ds_read_b128 v[212:215], v159 offset:39936
	global_load_lds_dwordx4 v[234:235], off
	v_lshl_add_u64 v[234:235], s[36:37], 0, v[134:135]
	s_mov_b32 m0, s44
	s_nop 0
	global_load_lds_dwordx4 v[234:235], off
	s_waitcnt vmcnt(8) lgkmcnt(0)
	s_barrier
	v_mfma_f32_16x16x32_bf16 v[124:127], v[128:131], v[176:179], v[124:127]
	v_mfma_f32_16x16x32_bf16 v[120:123], v[146:149], v[176:179], v[120:123]
	v_mfma_f32_16x16x32_bf16 v[108:111], v[128:131], v[188:191], v[108:111]
	v_mfma_f32_16x16x32_bf16 v[104:107], v[146:149], v[188:191], v[104:107]
	v_mfma_f32_16x16x32_bf16 v[96:99], v[128:131], v[200:203], v[96:99]
	v_mfma_f32_16x16x32_bf16 v[88:91], v[146:149], v[200:203], v[88:91]
	v_mfma_f32_16x16x32_bf16 v[80:83], v[128:131], v[208:211], v[80:83]
	v_mfma_f32_16x16x32_bf16 v[72:75], v[146:149], v[208:211], v[72:75]
	v_mfma_f32_16x16x32_bf16 v[124:127], v[142:145], v[180:183], v[124:127]
	v_mfma_f32_16x16x32_bf16 v[120:123], v[150:153], v[180:183], v[120:123]
	v_mfma_f32_16x16x32_bf16 v[108:111], v[142:145], v[196:199], v[108:111]
	v_mfma_f32_16x16x32_bf16 v[104:107], v[150:153], v[196:199], v[104:107]
	v_mfma_f32_16x16x32_bf16 v[96:99], v[142:145], v[204:207], v[96:99]
	v_mfma_f32_16x16x32_bf16 v[88:91], v[150:153], v[204:207], v[88:91]
	v_mfma_f32_16x16x32_bf16 v[80:83], v[142:145], v[212:215], v[80:83]
	v_mfma_f32_16x16x32_bf16 v[72:75], v[150:153], v[212:215], v[72:75]
	v_mfma_f32_16x16x32_bf16 v[116:119], v[160:163], v[176:179], v[116:119]
	v_mfma_f32_16x16x32_bf16 v[112:115], v[168:171], v[176:179], v[112:115]
	v_mfma_f32_16x16x32_bf16 v[100:103], v[160:163], v[188:191], v[100:103]
	v_mfma_f32_16x16x32_bf16 v[92:95], v[168:171], v[188:191], v[92:95]
	v_mfma_f32_16x16x32_bf16 v[84:87], v[160:163], v[200:203], v[84:87]
	v_mfma_f32_16x16x32_bf16 v[76:79], v[168:171], v[200:203], v[76:79]
	v_mfma_f32_16x16x32_bf16 v[68:71], v[160:163], v[208:211], v[68:71]
	v_mfma_f32_16x16x32_bf16 v[64:67], v[168:171], v[208:211], v[64:67]
	v_mfma_f32_16x16x32_bf16 v[116:119], v[164:167], v[180:183], v[116:119]
	v_mfma_f32_16x16x32_bf16 v[112:115], v[172:175], v[180:183], v[112:115]
	v_mfma_f32_16x16x32_bf16 v[100:103], v[164:167], v[196:199], v[100:103]
	v_mfma_f32_16x16x32_bf16 v[92:95], v[172:175], v[196:199], v[92:95]
	v_mfma_f32_16x16x32_bf16 v[84:87], v[164:167], v[204:207], v[84:87]
	v_mfma_f32_16x16x32_bf16 v[76:79], v[172:175], v[204:207], v[76:79]
	v_mfma_f32_16x16x32_bf16 v[68:71], v[164:167], v[212:215], v[68:71]
	v_mfma_f32_16x16x32_bf16 v[64:67], v[172:175], v[212:215], v[64:67]
	s_barrier
; #define PG8_STAGE(bufoff, gbase, voff) do { _Pragma("unroll") for (int _i = 0; _i < 2; ++_i) \
;         __builtin_amdgcn_global_load_lds((const unsigned*)((const char*)(gbase) + (voff)[_i]), (LAS unsigned*)(lds + (bufoff) + ldsw + _i * 8192), 16, 0, 0); } while (0)
; #define PG8_LDA(dst, b, h) do { _Pragma("unroll") for (int m = 0; m < 4; ++m) _Pragma("unroll") for (int k = 0; k < 2; ++k) dst[m][k] = *(const LAS bf16x8*)(lds + PG8_SA(b, h) + aoff + m * 2048 + k * 1024); } while (0)
; #define PG8_MMA(ai, bj, At, Bt) do { __builtin_amdgcn_s_setprio(1); _Pragma("unroll") for (int m = 0; m < 4; ++m) _Pragma("unroll") for (int n = 0; n < 2; ++n) _Pragma("unroll") for (int k = 0; k < 2; ++k) \
;         acc[ai][bj][m][n] = __builtin_amdgcn_mfma_f32_16x16x32_bf16(Bt[n][k], At[m][k], acc[ai][bj][m][n], 0, 0, 0); __builtin_amdgcn_s_setprio(0); } while (0)
; #define PG8_WAIT_V(n) asm volatile("s_waitcnt vmcnt(" #n ")" ::: "memory")
; #define PG8_WAIT_L(n) asm volatile("s_waitcnt lgkmcnt(" #n ")" ::: "memory")
; #define PG8_BAR __builtin_amdgcn_s_barrier()
; #define PG8_SCHED __builtin_amdgcn_sched_barrier(0)
; template <class Epi, class Sched>
; DI void gemm_phase(LAS unsigned char* lds, const int wv, const int lda, const int ldb, const Sched& S, const Epi& E) {
;     ...
;             PG8_LDA(At, 1, 1); PG8_STAGE(PG8_SB(1, 0), b3, voffB); PG8_STAGE(PG8_SB(1, 1), b3 + hstepB, voffB); PG8_STAGE(PG8_SA(1, 0), a3, voffA);
;             PG8_WAIT_V(8); PG8_WAIT_L(0); PG8_BAR; PG8_MMA(1, 0, At, B0); PG8_MMA(1, 1, At, B1); PG8_BAR; PG8_SCHED;
;         }
;         if (wr == 0) PG8_BAR;
	s_add_i32 s36, s54, s41
	v_lshl_add_u64 v[216:217], v[216:217], 0, s[28:29]
	s_mov_b32 m0, s36
	ds_read_b128 v[176:179], v159 offset:49152
	ds_read_b128 v[180:183], v159 offset:50176
	ds_read_b128 v[188:191], v159 offset:51200
	ds_read_b128 v[196:199], v159 offset:52224
	ds_read_b128 v[200:203], v159 offset:53248
	ds_read_b128 v[204:207], v159 offset:54272
	ds_read_b128 v[208:211], v159 offset:55296
	ds_read_b128 v[212:215], v159 offset:56320
	global_load_lds_dwordx4 v[216:217], off
	s_add_i32 m0, s36, 0x2000
	s_add_u32 s34, s34, 0x80080
	v_lshl_add_u64 v[216:217], v[218:219], 0, s[28:29]
	s_addc_u32 s35, s35, 0
	s_add_i32 s36, s55, s41
	global_load_lds_dwordx4 v[216:217], off
	v_lshl_add_u64 v[216:217], s[34:35], 0, v[184:185]
	s_mov_b32 m0, s36
	s_nop 0
	global_load_lds_dwordx4 v[216:217], off
	v_lshl_add_u64 v[216:217], s[34:35], 0, v[136:137]
	s_add_i32 m0, s36, 0x2000
	s_nop 0
	global_load_lds_dwordx4 v[216:217], off
	v_lshl_add_u64 v[216:217], v[220:221], 0, s[28:29]
	s_mov_b32 m0, s45
	s_nop 0
	global_load_lds_dwordx4 v[216:217], off
	v_lshl_add_u64 v[216:217], v[222:223], 0, s[28:29]
	s_mov_b32 m0, s46
	s_nop 0
	global_load_lds_dwordx4 v[216:217], off
	s_waitcnt vmcnt(8) lgkmcnt(0)
	s_barrier
	v_mfma_f32_16x16x32_bf16 v[60:63], v[128:131], v[176:179], v[60:63]
	v_mfma_f32_16x16x32_bf16 v[56:59], v[146:149], v[176:179], v[56:59]
	v_mfma_f32_16x16x32_bf16 v[48:51], v[128:131], v[188:191], v[48:51]
	v_mfma_f32_16x16x32_bf16 v[40:43], v[146:149], v[188:191], v[40:43]
	v_mfma_f32_16x16x32_bf16 v[32:35], v[128:131], v[200:203], v[32:35]
	v_mfma_f32_16x16x32_bf16 v[24:27], v[146:149], v[200:203], v[24:27]
	v_mfma_f32_16x16x32_bf16 v[16:19], v[128:131], v[208:211], v[16:19]
	v_mfma_f32_16x16x32_bf16 v[8:11], v[146:149], v[208:211], v[8:11]
	v_mfma_f32_16x16x32_bf16 v[60:63], v[142:145], v[180:183], v[60:63]
	v_mfma_f32_16x16x32_bf16 v[56:59], v[150:153], v[180:183], v[56:59]
	v_mfma_f32_16x16x32_bf16 v[48:51], v[142:145], v[196:199], v[48:51]
	v_mfma_f32_16x16x32_bf16 v[40:43], v[150:153], v[196:199], v[40:43]
	v_mfma_f32_16x16x32_bf16 v[32:35], v[142:145], v[204:207], v[32:35]
	v_mfma_f32_16x16x32_bf16 v[24:27], v[150:153], v[204:207], v[24:27]
	v_mfma_f32_16x16x32_bf16 v[16:19], v[142:145], v[212:215], v[16:19]
	v_mfma_f32_16x16x32_bf16 v[8:11], v[150:153], v[212:215], v[8:11]
	v_mfma_f32_16x16x32_bf16 v[52:55], v[160:163], v[176:179], v[52:55]
	v_mfma_f32_16x16x32_bf16 v[44:47], v[168:171], v[176:179], v[44:47]
	v_mfma_f32_16x16x32_bf16 v[36:39], v[160:163], v[188:191], v[36:39]
	v_mfma_f32_16x16x32_bf16 v[28:31], v[168:171], v[188:191], v[28:31]
	v_mfma_f32_16x16x32_bf16 v[20:23], v[160:163], v[200:203], v[20:23]
	v_mfma_f32_16x16x32_bf16 v[12:15], v[168:171], v[200:203], v[12:15]
	v_mfma_f32_16x16x32_bf16 v[4:7], v[160:163], v[208:211], v[4:7]
	v_mfma_f32_16x16x32_bf16 v[0:3], v[168:171], v[208:211], v[0:3]
	v_mfma_f32_16x16x32_bf16 v[52:55], v[164:167], v[180:183], v[52:55]
	v_mfma_f32_16x16x32_bf16 v[44:47], v[172:175], v[180:183], v[44:47]
	v_mfma_f32_16x16x32_bf16 v[36:39], v[164:167], v[196:199], v[36:39]
	v_mfma_f32_16x16x32_bf16 v[28:31], v[172:175], v[196:199], v[28:31]
	v_mfma_f32_16x16x32_bf16 v[20:23], v[164:167], v[204:207], v[20:23]
	v_mfma_f32_16x16x32_bf16 v[12:15], v[172:175], v[204:207], v[12:15]
	v_mfma_f32_16x16x32_bf16 v[4:7], v[164:167], v[212:215], v[4:7]
	v_mfma_f32_16x16x32_bf16 v[0:3], v[172:175], v[212:215], v[0:3]
	s_barrier
	s_add_i32 s53, s53, 2
	s_add_u32 s30, s30, 0x100
	s_addc_u32 s31, s31, 0
	s_add_u32 s19, s19, 0x100
	s_addc_u32 s52, s52, 0
	s_cmp_gt_u32 s53, 29
	s_cbranch_scc0 .LBB0_1299
	s_and_b64 vcc, exec, s[12:13]
	s_cbranch_vccz .LBB0_1302
	s_barrier

;     DI bool next(int i, Unit& u) const { const long L = (long)i * G + c; if (L >= T.nwg) return false; T.map((int)L, u.pm, u.pn); u.seg = 0; return true; }
;     DI bool next(int i, Unit& u) const { const int ti = i / 3; const long L = (long)ti * G + c; if (L >= T.nwg) return false; T.map((int)L, u.pm, u.pn); u.seg = i - 3 * ti; return true; }
;     DI const char* aptr(const Unit& u) const { return A + (size_t)u.pm * ta + (size_t)kofs(u.seg) * 2; }
;     DI const char* bptr(const Unit& u) const { return B + (size_t)u.pn * tb + (size_t)kofs(u.seg) * 2; }
; #define PG8_STAGE(bufoff, gbase, voff) do { _Pragma("unroll") for (int _i = 0; _i < 2; ++_i) \
;         __builtin_amdgcn_global_load_lds((const unsigned*)((const char*)(gbase) + (voff)[_i]), (LAS unsigned*)(lds + (bufoff) + ldsw + _i * 8192), 16, 0, 0); } while (0)
; #define PG8_LDA(dst, b, h) do { _Pragma("unroll") for (int m = 0; m < 4; ++m) _Pragma("unroll") for (int k = 0; k < 2; ++k) dst[m][k] = *(const LAS bf16x8*)(lds + PG8_SA(b, h) + aoff + m * 2048 + k * 1024); } while (0)
; #define PG8_LDB(dst, b, h) do { _Pragma("unroll") for (int n = 0; n < 2; ++n) _Pragma("unroll") for (int k = 0; k < 2; ++k) dst[n][k] = *(const LAS bf16x8*)(lds + PG8_SB(b, h) + boff + n * 2048 + k * 1024); } while (0)
; #define PG8_BAR __builtin_amdgcn_s_barrier()
; template <class Epi, class Sched>
; DI void gemm_phase(LAS unsigned char* lds, const int wv, const int lda, const int ldb, const Sched& S, const Epi& E) {
;     ...
;         const bool has_next = S.next(ui + 1, nxt);
;         const char* nA = has_next ? S.aptr(nxt) : cA; const char* nB = has_next ? S.bptr(nxt) : cB;
;         for (int t = 0; t < nt; t += 2) {
;             const bool last = (t == nt - 2);
;             const char* a1 = cA + (size_t)(t + 1) * kstep;
;             const char* a2 = last ? nA : cA + (size_t)(t + 2) * kstep; const char* b2 = last ? nB : cB + (size_t)(t + 2) * kstep;
;             const char* a3 = a2 + kstep; const char* b3 = b2 + kstep;
;             PG8_LDB(B0, 0, 0); PG8_LDB(B1, 0, 1); PG8_SCHED; PG8_LDA(At, 0, 0); PG8_STAGE(PG8_SA(1, 1), a1 + hstepA, voffA);
;             PG8_WAIT_V(8); PG8_WAIT_L(0); PG8_BAR; PG8_MMA(0, 0, At, B0); PG8_MMA(0, 1, At, B1); PG8_BAR; PG8_SCHED;
;             PG8_LDA(At, 0, 1); PG8_STAGE(PG8_SB(0, 0), b2, voffB); PG8_STAGE(PG8_SB(0, 1), b2 + hstepB, voffB); PG8_STAGE(PG8_SA(0, 0), a2, voffA);
.LBB0_1397:
	s_add_u32 s30, s26, 0xfff80080
	s_addc_u32 s31, s27, -1
	s_add_i32 s51, 0, 0x10000
	s_cmp_eq_u32 s50, 28
	s_cselect_b32 s35, s0, s31
	s_cselect_b32 s34, s1, s30
	v_add_u32_e32 v142, s51, v145
	s_cselect_b32 s31, s13, s49
	s_cselect_b32 s30, s15, s48
	s_add_i32 s54, 0, 0x14000
	ds_read_b128 v[138:141], v142
	ds_read_b128 v[148:151], v142 offset:1024
	ds_read_b128 v[152:155], v142 offset:2048
	ds_read_b128 v[156:159], v142 offset:3072
	v_add_u32_e32 v142, s54, v145
	ds_read_b128 v[160:163], v142
	ds_read_b128 v[164:167], v142 offset:1024
	ds_read_b128 v[168:171], v142 offset:2048
	ds_read_b128 v[172:175], v142 offset:3072
	v_lshl_add_u64 v[142:143], s[26:27], 0, v[134:135]
	s_add_i32 m0, s25, 0xc000
	ds_read_b128 v[176:179], v147
	ds_read_b128 v[180:183], v147 offset:1024
	ds_read_b128 v[188:191], v147 offset:2048
	ds_read_b128 v[196:199], v147 offset:3072
	ds_read_b128 v[200:203], v147 offset:4096
	ds_read_b128 v[204:207], v147 offset:5120
	ds_read_b128 v[208:211], v147 offset:6144
	ds_read_b128 v[212:215], v147 offset:7168
	global_load_lds_dwordx4 v[142:143], off
	v_lshl_add_u64 v[142:143], s[26:27], 0, v[136:137]
	s_add_i32 m0, s25, 0xe000
	s_nop 0
	global_load_lds_dwordx4 v[142:143], off
	s_waitcnt vmcnt(8) lgkmcnt(0)
	s_barrier
	v_mfma_f32_16x16x32_bf16 v[124:127], v[138:141], v[176:179], v[124:127]
	v_mfma_f32_16x16x32_bf16 v[120:123], v[152:155], v[176:179], v[120:123]
	v_mfma_f32_16x16x32_bf16 v[108:111], v[138:141], v[188:191], v[108:111]
	v_mfma_f32_16x16x32_bf16 v[104:107], v[152:155], v[188:191], v[104:107]
	v_mfma_f32_16x16x32_bf16 v[92:95], v[138:141], v[200:203], v[92:95]
	v_mfma_f32_16x16x32_bf16 v[88:91], v[152:155], v[200:203], v[88:91]
	v_mfma_f32_16x16x32_bf16 v[76:79], v[138:141], v[208:211], v[76:79]
	v_mfma_f32_16x16x32_bf16 v[72:75], v[152:155], v[208:211], v[72:75]
	v_mfma_f32_16x16x32_bf16 v[124:127], v[148:151], v[180:183], v[124:127]
	v_mfma_f32_16x16x32_bf16 v[120:123], v[156:159], v[180:183], v[120:123]
	v_mfma_f32_16x16x32_bf16 v[108:111], v[148:151], v[196:199], v[108:111]
	v_mfma_f32_16x16x32_bf16 v[104:107], v[156:159], v[196:199], v[104:107]
	v_mfma_f32_16x16x32_bf16 v[92:95], v[148:151], v[204:207], v[92:95]
	v_mfma_f32_16x16x32_bf16 v[88:91], v[156:159], v[204:207], v[88:91]
	v_mfma_f32_16x16x32_bf16 v[76:79], v[148:151], v[212:215], v[76:79]
	v_mfma_f32_16x16x32_bf16 v[72:75], v[156:159], v[212:215], v[72:75]
	v_mfma_f32_16x16x32_bf16 v[116:119], v[160:163], v[176:179], v[116:119]
	v_mfma_f32_16x16x32_bf16 v[112:115], v[168:171], v[176:179], v[112:115]
	v_mfma_f32_16x16x32_bf16 v[100:103], v[160:163], v[188:191], v[100:103]
	v_mfma_f32_16x16x32_bf16 v[96:99], v[168:171], v[188:191], v[96:99]
	v_mfma_f32_16x16x32_bf16 v[84:87], v[160:163], v[200:203], v[84:87]
	v_mfma_f32_16x16x32_bf16 v[80:83], v[168:171], v[200:203], v[80:83]
	v_mfma_f32_16x16x32_bf16 v[68:71], v[160:163], v[208:211], v[68:71]
	v_mfma_f32_16x16x32_bf16 v[64:67], v[168:171], v[208:211], v[64:67]
	v_mfma_f32_16x16x32_bf16 v[116:119], v[164:167], v[180:183], v[116:119]
	v_mfma_f32_16x16x32_bf16 v[112:115], v[172:175], v[180:183], v[112:115]
	v_mfma_f32_16x16x32_bf16 v[100:103], v[164:167], v[196:199], v[100:103]
	v_mfma_f32_16x16x32_bf16 v[96:99], v[172:175], v[196:199], v[96:99]
	v_mfma_f32_16x16x32_bf16 v[84:87], v[164:167], v[204:207], v[84:87]
	v_mfma_f32_16x16x32_bf16 v[80:83], v[172:175], v[204:207], v[80:83]
	v_mfma_f32_16x16x32_bf16 v[68:71], v[164:167], v[212:215], v[68:71]
	v_mfma_f32_16x16x32_bf16 v[64:67], v[172:175], v[212:215], v[64:67]
	s_barrier
	s_add_i32 s51, s51, s38
	v_lshl_add_u64 v[142:143], s[30:31], 0, v[184:185]
	s_mov_b32 m0, s51
	ds_read_b128 v[176:179], v147 offset:16384
	ds_read_b128 v[180:183], v147 offset:17408
	ds_read_b128 v[188:191], v147 offset:18432
	ds_read_b128 v[196:199], v147 offset:19456
	ds_read_b128 v[200:203], v147 offset:20480
	ds_read_b128 v[204:207], v147 offset:21504
	ds_read_b128 v[208:211], v147 offset:22528
	ds_read_b128 v[212:215], v147 offset:23552
	global_load_lds_dwordx4 v[142:143], off
	s_add_i32 m0, s51, 0x2000
	s_add_u32 s52, s30, 0x80000
	v_lshl_add_u64 v[216:217], s[30:31], 0, v[132:133]
	s_addc_u32 s53, s31, 0
	s_add_i32 s51, s54, s38
	global_load_lds_dwordx4 v[216:217], off
	v_lshl_add_u64 v[218:219], s[52:53], 0, v[184:185]
	s_mov_b32 m0, s51
	v_lshl_add_u64 v[220:221], s[34:35], 0, v[130:131]
	global_load_lds_dwordx4 v[218:219], off
	v_lshl_add_u64 v[218:219], s[52:53], 0, v[132:133]
	s_add_i32 m0, s51, 0x2000
	s_nop 0
	global_load_lds_dwordx4 v[218:219], off
	v_lshl_add_u64 v[218:219], s[34:35], 0, v[128:129]
	s_mov_b32 m0, s25
	s_nop 0
	global_load_lds_dwordx4 v[218:219], off
	s_mov_b32 m0, s39
	s_nop 0
	global_load_lds_dwordx4 v[220:221], off
	s_waitcnt vmcnt(8) lgkmcnt(0)
	s_barrier
; #define PG8_STAGE(bufoff, gbase, voff) do { _Pragma("unroll") for (int _i = 0; _i < 2; ++_i) \
;         __builtin_amdgcn_global_load_lds((const unsigned*)((const char*)(gbase) + (voff)[_i]), (LAS unsigned*)(lds + (bufoff) + ldsw + _i * 8192), 16, 0, 0); } while (0)
; #define PG8_LDA(dst, b, h) do { _Pragma("unroll") for (int m = 0; m < 4; ++m) _Pragma("unroll") for (int k = 0; k < 2; ++k) dst[m][k] = *(const LAS bf16x8*)(lds + PG8_SA(b, h) + aoff + m * 2048 + k * 1024); } while (0)
; #define PG8_LDB(dst, b, h) do { _Pragma("unroll") for (int n = 0; n < 2; ++n) _Pragma("unroll") for (int k = 0; k < 2; ++k) dst[n][k] = *(const LAS bf16x8*)(lds + PG8_SB(b, h) + boff + n * 2048 + k * 1024); } while (0)
; #define PG8_MMA(ai, bj, At, Bt) do { __builtin_amdgcn_s_setprio(1); _Pragma("unroll") for (int m = 0; m < 4; ++m) _Pragma("unroll") for (int n = 0; n < 2; ++n) _Pragma("unroll") for (int k = 0; k < 2; ++k) \
;         acc[ai][bj][m][n] = __builtin_amdgcn_mfma_f32_16x16x32_bf16(Bt[n][k], At[m][k], acc[ai][bj][m][n], 0, 0, 0); __builtin_amdgcn_s_setprio(0); } while (0)
; #define PG8_WAIT_V(n) asm volatile("s_waitcnt vmcnt(" #n ")" ::: "memory")
; #define PG8_WAIT_L(n) asm volatile("s_waitcnt lgkmcnt(" #n ")" ::: "memory")
; #define PG8_BAR __builtin_amdgcn_s_barrier()
; #define PG8_SCHED __builtin_amdgcn_sched_barrier(0)
; template <class Epi, class Sched>
; DI void gemm_phase(LAS unsigned char* lds, const int wv, const int lda, const int ldb, const Sched& S, const Epi& E) {
;     ...
;             PG8_WAIT_V(8); PG8_WAIT_L(0); PG8_BAR; PG8_MMA(1, 0, At, B0); PG8_MMA(1, 1, At, B1); PG8_BAR; PG8_SCHED;
;             PG8_LDB(B0, 1, 0); PG8_LDB(B1, 1, 1); PG8_SCHED; PG8_LDA(At, 1, 0); PG8_STAGE(PG8_SA(0, 1), a2 + hstepA, voffA);
;             PG8_WAIT_V(8); PG8_WAIT_L(0); PG8_BAR; PG8_MMA(0, 0, At, B0); PG8_MMA(0, 1, At, B1); PG8_BAR; PG8_SCHED;
	v_mfma_f32_16x16x32_bf16 v[60:63], v[138:141], v[176:179], v[60:63]
	v_mfma_f32_16x16x32_bf16 v[56:59], v[152:155], v[176:179], v[56:59]
	v_mfma_f32_16x16x32_bf16 v[44:47], v[138:141], v[188:191], v[44:47]
	v_mfma_f32_16x16x32_bf16 v[40:43], v[152:155], v[188:191], v[40:43]
	v_mfma_f32_16x16x32_bf16 v[28:31], v[138:141], v[200:203], v[28:31]
	v_mfma_f32_16x16x32_bf16 v[24:27], v[152:155], v[200:203], v[24:27]
	v_mfma_f32_16x16x32_bf16 v[12:15], v[138:141], v[208:211], v[12:15]
	v_mfma_f32_16x16x32_bf16 v[8:11], v[152:155], v[208:211], v[8:11]
	v_mfma_f32_16x16x32_bf16 v[60:63], v[148:151], v[180:183], v[60:63]
	v_mfma_f32_16x16x32_bf16 v[56:59], v[156:159], v[180:183], v[56:59]
	v_mfma_f32_16x16x32_bf16 v[44:47], v[148:151], v[196:199], v[44:47]
	v_mfma_f32_16x16x32_bf16 v[40:43], v[156:159], v[196:199], v[40:43]
	v_mfma_f32_16x16x32_bf16 v[28:31], v[148:151], v[204:207], v[28:31]
	v_mfma_f32_16x16x32_bf16 v[24:27], v[156:159], v[204:207], v[24:27]
	v_mfma_f32_16x16x32_bf16 v[12:15], v[148:151], v[212:215], v[12:15]
	v_mfma_f32_16x16x32_bf16 v[8:11], v[156:159], v[212:215], v[8:11]
	v_mfma_f32_16x16x32_bf16 v[52:55], v[160:163], v[176:179], v[52:55]
	v_mfma_f32_16x16x32_bf16 v[48:51], v[168:171], v[176:179], v[48:51]
	v_mfma_f32_16x16x32_bf16 v[36:39], v[160:163], v[188:191], v[36:39]
	v_mfma_f32_16x16x32_bf16 v[32:35], v[168:171], v[188:191], v[32:35]
	v_mfma_f32_16x16x32_bf16 v[20:23], v[160:163], v[200:203], v[20:23]
	v_mfma_f32_16x16x32_bf16 v[16:19], v[168:171], v[200:203], v[16:19]
	v_mfma_f32_16x16x32_bf16 v[4:7], v[160:163], v[208:211], v[4:7]
	v_mfma_f32_16x16x32_bf16 v[0:3], v[168:171], v[208:211], v[0:3]
	v_mfma_f32_16x16x32_bf16 v[52:55], v[164:167], v[180:183], v[52:55]
	v_mfma_f32_16x16x32_bf16 v[48:51], v[172:175], v[180:183], v[48:51]
	v_mfma_f32_16x16x32_bf16 v[36:39], v[164:167], v[196:199], v[36:39]
	v_mfma_f32_16x16x32_bf16 v[32:35], v[172:175], v[196:199], v[32:35]
	v_mfma_f32_16x16x32_bf16 v[20:23], v[164:167], v[204:207], v[20:23]
	v_mfma_f32_16x16x32_bf16 v[16:19], v[172:175], v[204:207], v[16:19]
	v_mfma_f32_16x16x32_bf16 v[4:7], v[164:167], v[212:215], v[4:7]
	v_mfma_f32_16x16x32_bf16 v[0:3], v[172:175], v[212:215], v[0:3]
	s_barrier
	s_add_i32 s51, 0, 0x18000
	s_add_i32 s52, 0, 0x1c000
	v_add_u32_e32 v156, s51, v145
	v_add_u32_e32 v172, s52, v145
	ds_read_b128 v[138:141], v156
	ds_read_b128 v[148:151], v156 offset:1024
	ds_read_b128 v[152:155], v156 offset:2048
	ds_read_b128 v[156:159], v156 offset:3072
	ds_read_b128 v[160:163], v172
	ds_read_b128 v[164:167], v172 offset:1024
	ds_read_b128 v[168:171], v172 offset:2048
	ds_read_b128 v[172:175], v172 offset:3072
	s_add_u32 s34, s34, 0x80000
	s_addc_u32 s35, s35, 0
	s_mov_b32 m0, s40
	v_lshl_add_u64 v[222:223], s[34:35], 0, v[128:129]
	ds_read_b128 v[176:179], v147 offset:32768
	ds_read_b128 v[180:183], v147 offset:33792
	ds_read_b128 v[188:191], v147 offset:34816
	ds_read_b128 v[196:199], v147 offset:35840
	ds_read_b128 v[200:203], v147 offset:36864
	ds_read_b128 v[204:207], v147 offset:37888
	ds_read_b128 v[208:211], v147 offset:38912
	ds_read_b128 v[212:215], v147 offset:39936
	global_load_lds_dwordx4 v[222:223], off
	v_lshl_add_u64 v[222:223], s[34:35], 0, v[130:131]
	s_mov_b32 m0, s41
	s_nop 0
	global_load_lds_dwordx4 v[222:223], off
	s_waitcnt vmcnt(8) lgkmcnt(0)
	s_barrier
	v_mfma_f32_16x16x32_bf16 v[124:127], v[138:141], v[176:179], v[124:127]
	v_mfma_f32_16x16x32_bf16 v[120:123], v[152:155], v[176:179], v[120:123]
	v_mfma_f32_16x16x32_bf16 v[108:111], v[138:141], v[188:191], v[108:111]
	v_mfma_f32_16x16x32_bf16 v[104:107], v[152:155], v[188:191], v[104:107]
	v_mfma_f32_16x16x32_bf16 v[92:95], v[138:141], v[200:203], v[92:95]
	v_mfma_f32_16x16x32_bf16 v[88:91], v[152:155], v[200:203], v[88:91]
	v_mfma_f32_16x16x32_bf16 v[76:79], v[138:141], v[208:211], v[76:79]
	v_mfma_f32_16x16x32_bf16 v[72:75], v[152:155], v[208:211], v[72:75]
	v_mfma_f32_16x16x32_bf16 v[124:127], v[148:151], v[180:183], v[124:127]
	v_mfma_f32_16x16x32_bf16 v[120:123], v[156:159], v[180:183], v[120:123]
	v_mfma_f32_16x16x32_bf16 v[108:111], v[148:151], v[196:199], v[108:111]
	v_mfma_f32_16x16x32_bf16 v[104:107], v[156:159], v[196:199], v[104:107]
	v_mfma_f32_16x16x32_bf16 v[92:95], v[148:151], v[204:207], v[92:95]
	v_mfma_f32_16x16x32_bf16 v[88:91], v[156:159], v[204:207], v[88:91]
	v_mfma_f32_16x16x32_bf16 v[76:79], v[148:151], v[212:215], v[76:79]
	v_mfma_f32_16x16x32_bf16 v[72:75], v[156:159], v[212:215], v[72:75]
	v_mfma_f32_16x16x32_bf16 v[116:119], v[160:163], v[176:179], v[116:119]
	v_mfma_f32_16x16x32_bf16 v[112:115], v[168:171], v[176:179], v[112:115]
	v_mfma_f32_16x16x32_bf16 v[100:103], v[160:163], v[188:191], v[100:103]
	v_mfma_f32_16x16x32_bf16 v[96:99], v[168:171], v[188:191], v[96:99]
	v_mfma_f32_16x16x32_bf16 v[84:87], v[160:163], v[200:203], v[84:87]
	v_mfma_f32_16x16x32_bf16 v[80:83], v[168:171], v[200:203], v[80:83]
	v_mfma_f32_16x16x32_bf16 v[68:71], v[160:163], v[208:211], v[68:71]
	v_mfma_f32_16x16x32_bf16 v[64:67], v[168:171], v[208:211], v[64:67]
	v_mfma_f32_16x16x32_bf16 v[116:119], v[164:167], v[180:183], v[116:119]
	v_mfma_f32_16x16x32_bf16 v[112:115], v[172:175], v[180:183], v[112:115]
	v_mfma_f32_16x16x32_bf16 v[100:103], v[164:167], v[196:199], v[100:103]
	v_mfma_f32_16x16x32_bf16 v[96:99], v[172:175], v[196:199], v[96:99]
	v_mfma_f32_16x16x32_bf16 v[84:87], v[164:167], v[204:207], v[84:87]
	v_mfma_f32_16x16x32_bf16 v[80:83], v[172:175], v[204:207], v[80:83]
	v_mfma_f32_16x16x32_bf16 v[68:71], v[164:167], v[212:215], v[68:71]
	v_mfma_f32_16x16x32_bf16 v[64:67], v[172:175], v[212:215], v[64:67]
	s_barrier
; #define PG8_STAGE(bufoff, gbase, voff) do { _Pragma("unroll") for (int _i = 0; _i < 2; ++_i) \
;         __builtin_amdgcn_global_load_lds((const unsigned*)((const char*)(gbase) + (voff)[_i]), (LAS unsigned*)(lds + (bufoff) + ldsw + _i * 8192), 16, 0, 0); } while (0)
; #define PG8_LDA(dst, b, h) do { _Pragma("unroll") for (int m = 0; m < 4; ++m) _Pragma("unroll") for (int k = 0; k < 2; ++k) dst[m][k] = *(const LAS bf16x8*)(lds + PG8_SA(b, h) + aoff + m * 2048 + k * 1024); } while (0)
; #define PG8_MMA(ai, bj, At, Bt) do { __builtin_amdgcn_s_setprio(1); _Pragma("unroll") for (int m = 0; m < 4; ++m) _Pragma("unroll") for (int n = 0; n < 2; ++n) _Pragma("unroll") for (int k = 0; k < 2; ++k) \
;         acc[ai][bj][m][n] = __builtin_amdgcn_mfma_f32_16x16x32_bf16(Bt[n][k], At[m][k], acc[ai][bj][m][n], 0, 0, 0); __builtin_amdgcn_s_setprio(0); } while (0)
; #define PG8_WAIT_V(n) asm volatile("s_waitcnt vmcnt(" #n ")" ::: "memory")
; #define PG8_WAIT_L(n) asm volatile("s_waitcnt lgkmcnt(" #n ")" ::: "memory")
; #define PG8_BAR __builtin_amdgcn_s_barrier()
; #define PG8_SCHED __builtin_amdgcn_sched_barrier(0)
; template <class Epi, class Sched>
; DI void gemm_phase(LAS unsigned char* lds, const int wv, const int lda, const int ldb, const Sched& S, const Epi& E) {
;     ...
;             PG8_LDA(At, 1, 1); PG8_STAGE(PG8_SB(1, 0), b3, voffB); PG8_STAGE(PG8_SB(1, 1), b3 + hstepB, voffB); PG8_STAGE(PG8_SA(1, 0), a3, voffA);
;             PG8_WAIT_V(8); PG8_WAIT_L(0); PG8_BAR; PG8_MMA(1, 0, At, B0); PG8_MMA(1, 1, At, B1); PG8_BAR; PG8_SCHED;
;         }
;         if (wr == 0) PG8_BAR;
	s_add_i32 s34, s51, s38
	v_lshl_add_u64 v[142:143], v[142:143], 0, s[28:29]
	s_mov_b32 m0, s34
	ds_read_b128 v[176:179], v147 offset:49152
	ds_read_b128 v[180:183], v147 offset:50176
	ds_read_b128 v[188:191], v147 offset:51200
	ds_read_b128 v[196:199], v147 offset:52224
	ds_read_b128 v[200:203], v147 offset:53248
	ds_read_b128 v[204:207], v147 offset:54272
	ds_read_b128 v[208:211], v147 offset:55296
	ds_read_b128 v[212:215], v147 offset:56320
	global_load_lds_dwordx4 v[142:143], off
	s_add_i32 m0, s34, 0x2000
	s_add_u32 s30, s30, 0x80080
	v_lshl_add_u64 v[142:143], v[216:217], 0, s[28:29]
	s_addc_u32 s31, s31, 0
	s_add_i32 s34, s52, s38
	global_load_lds_dwordx4 v[142:143], off
	v_lshl_add_u64 v[142:143], s[30:31], 0, v[184:185]
	s_mov_b32 m0, s34
	s_nop 0
	global_load_lds_dwordx4 v[142:143], off
	v_lshl_add_u64 v[142:143], s[30:31], 0, v[132:133]
	s_add_i32 m0, s34, 0x2000
	s_nop 0
	global_load_lds_dwordx4 v[142:143], off
	v_lshl_add_u64 v[142:143], v[218:219], 0, s[28:29]
	s_mov_b32 m0, s43
	s_nop 0
	global_load_lds_dwordx4 v[142:143], off
	v_lshl_add_u64 v[142:143], v[220:221], 0, s[28:29]
	s_mov_b32 m0, s44
	s_nop 0
	global_load_lds_dwordx4 v[142:143], off
	s_waitcnt vmcnt(8) lgkmcnt(0)
	s_barrier
	v_mfma_f32_16x16x32_bf16 v[60:63], v[138:141], v[176:179], v[60:63]
	v_mfma_f32_16x16x32_bf16 v[56:59], v[152:155], v[176:179], v[56:59]
	v_mfma_f32_16x16x32_bf16 v[44:47], v[138:141], v[188:191], v[44:47]
	v_mfma_f32_16x16x32_bf16 v[40:43], v[152:155], v[188:191], v[40:43]
	v_mfma_f32_16x16x32_bf16 v[28:31], v[138:141], v[200:203], v[28:31]
	v_mfma_f32_16x16x32_bf16 v[24:27], v[152:155], v[200:203], v[24:27]
	v_mfma_f32_16x16x32_bf16 v[12:15], v[138:141], v[208:211], v[12:15]
	v_mfma_f32_16x16x32_bf16 v[8:11], v[152:155], v[208:211], v[8:11]
	v_mfma_f32_16x16x32_bf16 v[60:63], v[148:151], v[180:183], v[60:63]
	v_mfma_f32_16x16x32_bf16 v[56:59], v[156:159], v[180:183], v[56:59]
	v_mfma_f32_16x16x32_bf16 v[44:47], v[148:151], v[196:199], v[44:47]
	v_mfma_f32_16x16x32_bf16 v[40:43], v[156:159], v[196:199], v[40:43]
	v_mfma_f32_16x16x32_bf16 v[28:31], v[148:151], v[204:207], v[28:31]
	v_mfma_f32_16x16x32_bf16 v[24:27], v[156:159], v[204:207], v[24:27]
	v_mfma_f32_16x16x32_bf16 v[12:15], v[148:151], v[212:215], v[12:15]
	v_mfma_f32_16x16x32_bf16 v[8:11], v[156:159], v[212:215], v[8:11]
	v_mfma_f32_16x16x32_bf16 v[52:55], v[160:163], v[176:179], v[52:55]
	v_mfma_f32_16x16x32_bf16 v[48:51], v[168:171], v[176:179], v[48:51]
	v_mfma_f32_16x16x32_bf16 v[36:39], v[160:163], v[188:191], v[36:39]
	v_mfma_f32_16x16x32_bf16 v[32:35], v[168:171], v[188:191], v[32:35]
	v_mfma_f32_16x16x32_bf16 v[20:23], v[160:163], v[200:203], v[20:23]
	v_mfma_f32_16x16x32_bf16 v[16:19], v[168:171], v[200:203], v[16:19]
	v_mfma_f32_16x16x32_bf16 v[4:7], v[160:163], v[208:211], v[4:7]
	v_mfma_f32_16x16x32_bf16 v[0:3], v[168:171], v[208:211], v[0:3]
	v_mfma_f32_16x16x32_bf16 v[52:55], v[164:167], v[180:183], v[52:55]
	v_mfma_f32_16x16x32_bf16 v[48:51], v[172:175], v[180:183], v[48:51]
	v_mfma_f32_16x16x32_bf16 v[36:39], v[164:167], v[196:199], v[36:39]
	v_mfma_f32_16x16x32_bf16 v[32:35], v[172:175], v[196:199], v[32:35]
	v_mfma_f32_16x16x32_bf16 v[20:23], v[164:167], v[204:207], v[20:23]
	v_mfma_f32_16x16x32_bf16 v[16:19], v[172:175], v[204:207], v[16:19]
	v_mfma_f32_16x16x32_bf16 v[4:7], v[164:167], v[212:215], v[4:7]
	v_mfma_f32_16x16x32_bf16 v[0:3], v[172:175], v[212:215], v[0:3]
	s_barrier
	s_add_i32 s50, s50, 2
	s_add_u32 s26, s26, 0x100
	s_addc_u32 s27, s27, 0
	s_add_u32 s48, s48, 0x100
	s_addc_u32 s49, s49, 0
	s_cmp_gt_u32 s50, 29
	s_cbranch_scc0 .LBB0_1397
	s_and_b64 vcc, exec, s[10:11]
	s_cbranch_vccz .LBB0_1400
	s_barrier

; #define PG8_STAGE(bufoff, gbase, voff) do { _Pragma("unroll") for (int _i = 0; _i < 2; ++_i) \
;         __builtin_amdgcn_global_load_lds((const unsigned*)((const char*)(gbase) + (voff)[_i]), (LAS unsigned*)(lds + (bufoff) + ldsw + _i * 8192), 16, 0, 0); } while (0)
; #define PG8_LDA(dst, b, h) do { _Pragma("unroll") for (int m = 0; m < 4; ++m) _Pragma("unroll") for (int k = 0; k < 2; ++k) dst[m][k] = *(const LAS bf16x8*)(lds + PG8_SA(b, h) + aoff + m * 2048 + k * 1024); } while (0)
; #define PG8_LDB(dst, b, h) do { _Pragma("unroll") for (int n = 0; n < 2; ++n) _Pragma("unroll") for (int k = 0; k < 2; ++k) dst[n][k] = *(const LAS bf16x8*)(lds + PG8_SB(b, h) + boff + n * 2048 + k * 1024); } while (0)
; #define PG8_MMA(ai, bj, At, Bt) do { __builtin_amdgcn_s_setprio(1); _Pragma("unroll") for (int m = 0; m < 4; ++m) _Pragma("unroll") for (int n = 0; n < 2; ++n) _Pragma("unroll") for (int k = 0; k < 2; ++k) \
;         acc[ai][bj][m][n] = __builtin_amdgcn_mfma_f32_16x16x32_bf16(Bt[n][k], At[m][k], acc[ai][bj][m][n], 0, 0, 0); __builtin_amdgcn_s_setprio(0); } while (0)
; #define PG8_WAIT_V(n) asm volatile("s_waitcnt vmcnt(" #n ")" ::: "memory")
; #define PG8_WAIT_L(n) asm volatile("s_waitcnt lgkmcnt(" #n ")" ::: "memory")
; #define PG8_BAR __builtin_amdgcn_s_barrier()
; #define PG8_SCHED __builtin_amdgcn_sched_barrier(0)
; template <class Epi, class Sched>
; DI void gemm_phase(LAS unsigned char* lds, const int wv, const int lda, const int ldb, const Sched& S, const Epi& E) {
;     ...
;         for (int t = 0; t < nt; t += 2) {
;             const bool last = (t == nt - 2);
;             const char* a1 = cA + (size_t)(t + 1) * kstep;
;             const char* a2 = last ? nA : cA + (size_t)(t + 2) * kstep; const char* b2 = last ? nB : cB + (size_t)(t + 2) * kstep;
;             const char* a3 = a2 + kstep; const char* b3 = b2 + kstep;
;             PG8_LDB(B0, 0, 0); PG8_LDB(B1, 0, 1); PG8_SCHED; PG8_LDA(At, 0, 0); PG8_STAGE(PG8_SA(1, 1), a1 + hstepA, voffA);
;             PG8_WAIT_V(8); PG8_WAIT_L(0); PG8_BAR; PG8_MMA(0, 0, At, B0); PG8_MMA(0, 1, At, B1); PG8_BAR; PG8_SCHED;
;             PG8_LDA(At, 0, 1); PG8_STAGE(PG8_SB(0, 0), b2, voffB); PG8_STAGE(PG8_SB(0, 1), b2 + hstepB, voffB); PG8_STAGE(PG8_SA(0, 0), a2, voffA);
;             PG8_WAIT_V(8); PG8_WAIT_L(0); PG8_BAR; PG8_MMA(1, 0, At, B0); PG8_MMA(1, 1, At, B1); PG8_BAR; PG8_SCHED;
.LBB0_1477:
	s_add_u32 s36, s34, 0xffe00080
	s_addc_u32 s37, s35, -1
	s_add_i32 s56, 0, 0x10000
	s_cmpk_eq_i32 s55, 0x7c
	s_cselect_b32 s39, s0, s37
	s_cselect_b32 s38, s1, s36
	s_cselect_b32 s37, s11, s54
	s_cselect_b32 s36, s19, s23
	s_add_i32 s58, 0, 0x14000
	v_add_u32_e32 v150, s56, v155
	v_add_u32_e32 v172, s58, v155
	ds_read_b128 v[128:131], v150
	ds_read_b128 v[142:145], v150 offset:1024
	ds_read_b128 v[146:149], v150 offset:2048
	ds_read_b128 v[150:153], v150 offset:3072
	ds_read_b128 v[160:163], v172
	ds_read_b128 v[164:167], v172 offset:1024
	ds_read_b128 v[168:171], v172 offset:2048
	ds_read_b128 v[172:175], v172 offset:3072
	v_lshl_add_u64 v[216:217], s[34:35], 0, v[138:139]
	s_add_i32 m0, s31, 0xc000
	ds_read_b128 v[176:179], v159
	ds_read_b128 v[180:183], v159 offset:1024
	ds_read_b128 v[188:191], v159 offset:2048
	ds_read_b128 v[196:199], v159 offset:3072
	ds_read_b128 v[200:203], v159 offset:4096
	ds_read_b128 v[204:207], v159 offset:5120
	ds_read_b128 v[208:211], v159 offset:6144
	ds_read_b128 v[212:215], v159 offset:7168
	global_load_lds_dwordx4 v[216:217], off
	v_lshl_add_u64 v[216:217], s[34:35], 0, v[140:141]
	s_add_i32 m0, s31, 0xe000
	s_nop 0
	global_load_lds_dwordx4 v[216:217], off
	s_waitcnt vmcnt(8) lgkmcnt(0)
	s_barrier
	v_mfma_f32_16x16x32_bf16 v[124:127], v[128:131], v[176:179], v[124:127]
	v_mfma_f32_16x16x32_bf16 v[120:123], v[146:149], v[176:179], v[120:123]
	v_mfma_f32_16x16x32_bf16 v[108:111], v[128:131], v[188:191], v[108:111]
	v_mfma_f32_16x16x32_bf16 v[104:107], v[146:149], v[188:191], v[104:107]
	v_mfma_f32_16x16x32_bf16 v[96:99], v[128:131], v[200:203], v[96:99]
	v_mfma_f32_16x16x32_bf16 v[88:91], v[146:149], v[200:203], v[88:91]
	v_mfma_f32_16x16x32_bf16 v[80:83], v[128:131], v[208:211], v[80:83]
	v_mfma_f32_16x16x32_bf16 v[72:75], v[146:149], v[208:211], v[72:75]
	v_mfma_f32_16x16x32_bf16 v[124:127], v[142:145], v[180:183], v[124:127]
	v_mfma_f32_16x16x32_bf16 v[120:123], v[150:153], v[180:183], v[120:123]
	v_mfma_f32_16x16x32_bf16 v[108:111], v[142:145], v[196:199], v[108:111]
	v_mfma_f32_16x16x32_bf16 v[104:107], v[150:153], v[196:199], v[104:107]
	v_mfma_f32_16x16x32_bf16 v[96:99], v[142:145], v[204:207], v[96:99]
	v_mfma_f32_16x16x32_bf16 v[88:91], v[150:153], v[204:207], v[88:91]
	v_mfma_f32_16x16x32_bf16 v[80:83], v[142:145], v[212:215], v[80:83]
	v_mfma_f32_16x16x32_bf16 v[72:75], v[150:153], v[212:215], v[72:75]
	v_mfma_f32_16x16x32_bf16 v[116:119], v[160:163], v[176:179], v[116:119]
	v_mfma_f32_16x16x32_bf16 v[112:115], v[168:171], v[176:179], v[112:115]
	v_mfma_f32_16x16x32_bf16 v[100:103], v[160:163], v[188:191], v[100:103]
	v_mfma_f32_16x16x32_bf16 v[92:95], v[168:171], v[188:191], v[92:95]
	v_mfma_f32_16x16x32_bf16 v[84:87], v[160:163], v[200:203], v[84:87]
	v_mfma_f32_16x16x32_bf16 v[76:79], v[168:171], v[200:203], v[76:79]
	v_mfma_f32_16x16x32_bf16 v[68:71], v[160:163], v[208:211], v[68:71]
	v_mfma_f32_16x16x32_bf16 v[64:67], v[168:171], v[208:211], v[64:67]
	v_mfma_f32_16x16x32_bf16 v[116:119], v[164:167], v[180:183], v[116:119]
	v_mfma_f32_16x16x32_bf16 v[112:115], v[172:175], v[180:183], v[112:115]
	v_mfma_f32_16x16x32_bf16 v[100:103], v[164:167], v[196:199], v[100:103]
	v_mfma_f32_16x16x32_bf16 v[92:95], v[172:175], v[196:199], v[92:95]
	v_mfma_f32_16x16x32_bf16 v[84:87], v[164:167], v[204:207], v[84:87]
	v_mfma_f32_16x16x32_bf16 v[76:79], v[172:175], v[204:207], v[76:79]
	v_mfma_f32_16x16x32_bf16 v[68:71], v[164:167], v[212:215], v[68:71]
	v_mfma_f32_16x16x32_bf16 v[64:67], v[172:175], v[212:215], v[64:67]
	s_barrier
	s_add_i32 s56, s56, s43
	v_lshl_add_u64 v[216:217], s[36:37], 0, v[184:185]
	s_mov_b32 m0, s56
	ds_read_b128 v[176:179], v159 offset:16384
	ds_read_b128 v[180:183], v159 offset:17408
	ds_read_b128 v[188:191], v159 offset:18432
	ds_read_b128 v[196:199], v159 offset:19456
	ds_read_b128 v[200:203], v159 offset:20480
	ds_read_b128 v[204:207], v159 offset:21504
	ds_read_b128 v[208:211], v159 offset:22528
	ds_read_b128 v[212:215], v159 offset:23552
	global_load_lds_dwordx4 v[216:217], off
	s_add_i32 m0, s56, 0x2000
	s_add_u32 s56, s36, 0x200000
	v_lshl_add_u64 v[218:219], s[36:37], 0, v[136:137]
	s_addc_u32 s57, s37, 0
	s_add_i32 s58, s58, s43
	global_load_lds_dwordx4 v[218:219], off
	v_lshl_add_u64 v[220:221], s[56:57], 0, v[184:185]
	s_mov_b32 m0, s58
	v_lshl_add_u64 v[222:223], s[38:39], 0, v[134:135]
	global_load_lds_dwordx4 v[220:221], off
	v_lshl_add_u64 v[220:221], s[56:57], 0, v[136:137]
	s_add_i32 m0, s58, 0x2000
	s_nop 0
	global_load_lds_dwordx4 v[220:221], off
	v_lshl_add_u64 v[220:221], s[38:39], 0, v[132:133]
	s_mov_b32 m0, s31
	s_nop 0
	global_load_lds_dwordx4 v[220:221], off
	s_mov_b32 m0, s44
	s_nop 0
	global_load_lds_dwordx4 v[222:223], off
	s_waitcnt vmcnt(8) lgkmcnt(0)
	s_barrier
; #define PG8_STAGE(bufoff, gbase, voff) do { _Pragma("unroll") for (int _i = 0; _i < 2; ++_i) \
;         __builtin_amdgcn_global_load_lds((const unsigned*)((const char*)(gbase) + (voff)[_i]), (LAS unsigned*)(lds + (bufoff) + ldsw + _i * 8192), 16, 0, 0); } while (0)
; #define PG8_LDA(dst, b, h) do { _Pragma("unroll") for (int m = 0; m < 4; ++m) _Pragma("unroll") for (int k = 0; k < 2; ++k) dst[m][k] = *(const LAS bf16x8*)(lds + PG8_SA(b, h) + aoff + m * 2048 + k * 1024); } while (0)
; #define PG8_LDB(dst, b, h) do { _Pragma("unroll") for (int n = 0; n < 2; ++n) _Pragma("unroll") for (int k = 0; k < 2; ++k) dst[n][k] = *(const LAS bf16x8*)(lds + PG8_SB(b, h) + boff + n * 2048 + k * 1024); } while (0)
; #define PG8_MMA(ai, bj, At, Bt) do { __builtin_amdgcn_s_setprio(1); _Pragma("unroll") for (int m = 0; m < 4; ++m) _Pragma("unroll") for (int n = 0; n < 2; ++n) _Pragma("unroll") for (int k = 0; k < 2; ++k) \
;         acc[ai][bj][m][n] = __builtin_amdgcn_mfma_f32_16x16x32_bf16(Bt[n][k], At[m][k], acc[ai][bj][m][n], 0, 0, 0); __builtin_amdgcn_s_setprio(0); } while (0)
; #define PG8_WAIT_V(n) asm volatile("s_waitcnt vmcnt(" #n ")" ::: "memory")
; #define PG8_WAIT_L(n) asm volatile("s_waitcnt lgkmcnt(" #n ")" ::: "memory")
; #define PG8_BAR __builtin_amdgcn_s_barrier()
; #define PG8_SCHED __builtin_amdgcn_sched_barrier(0)
; template <class Epi, class Sched>
; DI void gemm_phase(LAS unsigned char* lds, const int wv, const int lda, const int ldb, const Sched& S, const Epi& E) {
;     ...
;             PG8_WAIT_V(8); PG8_WAIT_L(0); PG8_BAR; PG8_MMA(1, 0, At, B0); PG8_MMA(1, 1, At, B1); PG8_BAR; PG8_SCHED;
;             PG8_LDB(B0, 1, 0); PG8_LDB(B1, 1, 1); PG8_SCHED; PG8_LDA(At, 1, 0); PG8_STAGE(PG8_SA(0, 1), a2 + hstepA, voffA);
;             PG8_WAIT_V(8); PG8_WAIT_L(0); PG8_BAR; PG8_MMA(0, 0, At, B0); PG8_MMA(0, 1, At, B1); PG8_BAR; PG8_SCHED;
	v_mfma_f32_16x16x32_bf16 v[60:63], v[128:131], v[176:179], v[60:63]
	v_mfma_f32_16x16x32_bf16 v[56:59], v[146:149], v[176:179], v[56:59]
	v_mfma_f32_16x16x32_bf16 v[48:51], v[128:131], v[188:191], v[48:51]
	v_mfma_f32_16x16x32_bf16 v[40:43], v[146:149], v[188:191], v[40:43]
	v_mfma_f32_16x16x32_bf16 v[32:35], v[128:131], v[200:203], v[32:35]
	v_mfma_f32_16x16x32_bf16 v[24:27], v[146:149], v[200:203], v[24:27]
	v_mfma_f32_16x16x32_bf16 v[16:19], v[128:131], v[208:211], v[16:19]
	v_mfma_f32_16x16x32_bf16 v[8:11], v[146:149], v[208:211], v[8:11]
	v_mfma_f32_16x16x32_bf16 v[60:63], v[142:145], v[180:183], v[60:63]
	v_mfma_f32_16x16x32_bf16 v[56:59], v[150:153], v[180:183], v[56:59]
	v_mfma_f32_16x16x32_bf16 v[48:51], v[142:145], v[196:199], v[48:51]
	v_mfma_f32_16x16x32_bf16 v[40:43], v[150:153], v[196:199], v[40:43]
	v_mfma_f32_16x16x32_bf16 v[32:35], v[142:145], v[204:207], v[32:35]
	v_mfma_f32_16x16x32_bf16 v[24:27], v[150:153], v[204:207], v[24:27]
	v_mfma_f32_16x16x32_bf16 v[16:19], v[142:145], v[212:215], v[16:19]
	v_mfma_f32_16x16x32_bf16 v[8:11], v[150:153], v[212:215], v[8:11]
	v_mfma_f32_16x16x32_bf16 v[52:55], v[160:163], v[176:179], v[52:55]
	v_mfma_f32_16x16x32_bf16 v[44:47], v[168:171], v[176:179], v[44:47]
	v_mfma_f32_16x16x32_bf16 v[36:39], v[160:163], v[188:191], v[36:39]
	v_mfma_f32_16x16x32_bf16 v[28:31], v[168:171], v[188:191], v[28:31]
	v_mfma_f32_16x16x32_bf16 v[20:23], v[160:163], v[200:203], v[20:23]
	v_mfma_f32_16x16x32_bf16 v[12:15], v[168:171], v[200:203], v[12:15]
	v_mfma_f32_16x16x32_bf16 v[4:7], v[160:163], v[208:211], v[4:7]
	v_mfma_f32_16x16x32_bf16 v[0:3], v[168:171], v[208:211], v[0:3]
	v_mfma_f32_16x16x32_bf16 v[52:55], v[164:167], v[180:183], v[52:55]
	v_mfma_f32_16x16x32_bf16 v[44:47], v[172:175], v[180:183], v[44:47]
	v_mfma_f32_16x16x32_bf16 v[36:39], v[164:167], v[196:199], v[36:39]
	v_mfma_f32_16x16x32_bf16 v[28:31], v[172:175], v[196:199], v[28:31]
	v_mfma_f32_16x16x32_bf16 v[20:23], v[164:167], v[204:207], v[20:23]
	v_mfma_f32_16x16x32_bf16 v[12:15], v[172:175], v[204:207], v[12:15]
	v_mfma_f32_16x16x32_bf16 v[4:7], v[164:167], v[212:215], v[4:7]
	v_mfma_f32_16x16x32_bf16 v[0:3], v[172:175], v[212:215], v[0:3]
	s_barrier
	s_add_i32 s56, 0, 0x18000
	s_add_i32 s57, 0, 0x1c000
	v_add_u32_e32 v150, s56, v155
	v_add_u32_e32 v172, s57, v155
	ds_read_b128 v[128:131], v150
	ds_read_b128 v[142:145], v150 offset:1024
	ds_read_b128 v[146:149], v150 offset:2048
	ds_read_b128 v[150:153], v150 offset:3072
	ds_read_b128 v[160:163], v172
	ds_read_b128 v[164:167], v172 offset:1024
	ds_read_b128 v[168:171], v172 offset:2048
	ds_read_b128 v[172:175], v172 offset:3072
	s_add_u32 s38, s38, 0x200000
	s_addc_u32 s39, s39, 0
	s_mov_b32 m0, s45
	v_lshl_add_u64 v[234:235], s[38:39], 0, v[132:133]
	ds_read_b128 v[176:179], v159 offset:32768
	ds_read_b128 v[180:183], v159 offset:33792
	ds_read_b128 v[188:191], v159 offset:34816
	ds_read_b128 v[196:199], v159 offset:35840
	ds_read_b128 v[200:203], v159 offset:36864
	ds_read_b128 v[204:207], v159 offset:37888
	ds_read_b128 v[208:211], v159 offset:38912
	ds_read_b128 v[212:215], v159 offset:39936
	global_load_lds_dwordx4 v[234:235], off
	v_lshl_add_u64 v[234:235], s[38:39], 0, v[134:135]
	s_mov_b32 m0, s46
	s_nop 0
	global_load_lds_dwordx4 v[234:235], off
	s_waitcnt vmcnt(8) lgkmcnt(0)
	s_barrier
	v_mfma_f32_16x16x32_bf16 v[124:127], v[128:131], v[176:179], v[124:127]
	v_mfma_f32_16x16x32_bf16 v[120:123], v[146:149], v[176:179], v[120:123]
	v_mfma_f32_16x16x32_bf16 v[108:111], v[128:131], v[188:191], v[108:111]
	v_mfma_f32_16x16x32_bf16 v[104:107], v[146:149], v[188:191], v[104:107]
	v_mfma_f32_16x16x32_bf16 v[96:99], v[128:131], v[200:203], v[96:99]
	v_mfma_f32_16x16x32_bf16 v[88:91], v[146:149], v[200:203], v[88:91]
	v_mfma_f32_16x16x32_bf16 v[80:83], v[128:131], v[208:211], v[80:83]
	v_mfma_f32_16x16x32_bf16 v[72:75], v[146:149], v[208:211], v[72:75]
	v_mfma_f32_16x16x32_bf16 v[124:127], v[142:145], v[180:183], v[124:127]
	v_mfma_f32_16x16x32_bf16 v[120:123], v[150:153], v[180:183], v[120:123]
	v_mfma_f32_16x16x32_bf16 v[108:111], v[142:145], v[196:199], v[108:111]
	v_mfma_f32_16x16x32_bf16 v[104:107], v[150:153], v[196:199], v[104:107]
	v_mfma_f32_16x16x32_bf16 v[96:99], v[142:145], v[204:207], v[96:99]
	v_mfma_f32_16x16x32_bf16 v[88:91], v[150:153], v[204:207], v[88:91]
	v_mfma_f32_16x16x32_bf16 v[80:83], v[142:145], v[212:215], v[80:83]
	v_mfma_f32_16x16x32_bf16 v[72:75], v[150:153], v[212:215], v[72:75]
	v_mfma_f32_16x16x32_bf16 v[116:119], v[160:163], v[176:179], v[116:119]
	v_mfma_f32_16x16x32_bf16 v[112:115], v[168:171], v[176:179], v[112:115]
	v_mfma_f32_16x16x32_bf16 v[100:103], v[160:163], v[188:191], v[100:103]
	v_mfma_f32_16x16x32_bf16 v[92:95], v[168:171], v[188:191], v[92:95]
	v_mfma_f32_16x16x32_bf16 v[84:87], v[160:163], v[200:203], v[84:87]
	v_mfma_f32_16x16x32_bf16 v[76:79], v[168:171], v[200:203], v[76:79]
	v_mfma_f32_16x16x32_bf16 v[68:71], v[160:163], v[208:211], v[68:71]
	v_mfma_f32_16x16x32_bf16 v[64:67], v[168:171], v[208:211], v[64:67]
	v_mfma_f32_16x16x32_bf16 v[116:119], v[164:167], v[180:183], v[116:119]
	v_mfma_f32_16x16x32_bf16 v[112:115], v[172:175], v[180:183], v[112:115]
	v_mfma_f32_16x16x32_bf16 v[100:103], v[164:167], v[196:199], v[100:103]
	v_mfma_f32_16x16x32_bf16 v[92:95], v[172:175], v[196:199], v[92:95]
	v_mfma_f32_16x16x32_bf16 v[84:87], v[164:167], v[204:207], v[84:87]
	v_mfma_f32_16x16x32_bf16 v[76:79], v[172:175], v[204:207], v[76:79]
	v_mfma_f32_16x16x32_bf16 v[68:71], v[164:167], v[212:215], v[68:71]
	v_mfma_f32_16x16x32_bf16 v[64:67], v[172:175], v[212:215], v[64:67]
	s_barrier
; #define PG8_STAGE(bufoff, gbase, voff) do { _Pragma("unroll") for (int _i = 0; _i < 2; ++_i) \
;         __builtin_amdgcn_global_load_lds((const unsigned*)((const char*)(gbase) + (voff)[_i]), (LAS unsigned*)(lds + (bufoff) + ldsw + _i * 8192), 16, 0, 0); } while (0)
; #define PG8_LDA(dst, b, h) do { _Pragma("unroll") for (int m = 0; m < 4; ++m) _Pragma("unroll") for (int k = 0; k < 2; ++k) dst[m][k] = *(const LAS bf16x8*)(lds + PG8_SA(b, h) + aoff + m * 2048 + k * 1024); } while (0)
; #define PG8_MMA(ai, bj, At, Bt) do { __builtin_amdgcn_s_setprio(1); _Pragma("unroll") for (int m = 0; m < 4; ++m) _Pragma("unroll") for (int n = 0; n < 2; ++n) _Pragma("unroll") for (int k = 0; k < 2; ++k) \
;         acc[ai][bj][m][n] = __builtin_amdgcn_mfma_f32_16x16x32_bf16(Bt[n][k], At[m][k], acc[ai][bj][m][n], 0, 0, 0); __builtin_amdgcn_s_setprio(0); } while (0)
; #define PG8_WAIT_V(n) asm volatile("s_waitcnt vmcnt(" #n ")" ::: "memory")
; #define PG8_WAIT_L(n) asm volatile("s_waitcnt lgkmcnt(" #n ")" ::: "memory")
; #define PG8_BAR __builtin_amdgcn_s_barrier()
; #define PG8_SCHED __builtin_amdgcn_sched_barrier(0)
; template <class Epi, class Sched>
; DI void gemm_phase(LAS unsigned char* lds, const int wv, const int lda, const int ldb, const Sched& S, const Epi& E) {
;     ...
;             PG8_LDA(At, 1, 1); PG8_STAGE(PG8_SB(1, 0), b3, voffB); PG8_STAGE(PG8_SB(1, 1), b3 + hstepB, voffB); PG8_STAGE(PG8_SA(1, 0), a3, voffA);
;             PG8_WAIT_V(8); PG8_WAIT_L(0); PG8_BAR; PG8_MMA(1, 0, At, B0); PG8_MMA(1, 1, At, B1); PG8_BAR; PG8_SCHED;
;         }
;         if (wr == 0) PG8_BAR;
	s_add_i32 s38, s56, s43
	v_lshl_add_u64 v[216:217], v[216:217], 0, s[28:29]
	s_mov_b32 m0, s38
	ds_read_b128 v[176:179], v159 offset:49152
	ds_read_b128 v[180:183], v159 offset:50176
	ds_read_b128 v[188:191], v159 offset:51200
	ds_read_b128 v[196:199], v159 offset:52224
	ds_read_b128 v[200:203], v159 offset:53248
	ds_read_b128 v[204:207], v159 offset:54272
	ds_read_b128 v[208:211], v159 offset:55296
	ds_read_b128 v[212:215], v159 offset:56320
	global_load_lds_dwordx4 v[216:217], off
	s_add_i32 m0, s38, 0x2000
	s_add_u32 s36, s36, 0x200080
	v_lshl_add_u64 v[216:217], v[218:219], 0, s[28:29]
	s_addc_u32 s37, s37, 0
	s_add_i32 s38, s57, s43
	global_load_lds_dwordx4 v[216:217], off
	v_lshl_add_u64 v[216:217], s[36:37], 0, v[184:185]
	s_mov_b32 m0, s38
	s_nop 0
	global_load_lds_dwordx4 v[216:217], off
	v_lshl_add_u64 v[216:217], s[36:37], 0, v[136:137]
	s_add_i32 m0, s38, 0x2000
	s_nop 0
	global_load_lds_dwordx4 v[216:217], off
	v_lshl_add_u64 v[216:217], v[220:221], 0, s[28:29]
	s_mov_b32 m0, s47
	s_nop 0
	global_load_lds_dwordx4 v[216:217], off
	v_lshl_add_u64 v[216:217], v[222:223], 0, s[28:29]
	s_mov_b32 m0, s48
	s_nop 0
	global_load_lds_dwordx4 v[216:217], off
	s_waitcnt vmcnt(8) lgkmcnt(0)
	s_barrier
	v_mfma_f32_16x16x32_bf16 v[60:63], v[128:131], v[176:179], v[60:63]
	v_mfma_f32_16x16x32_bf16 v[56:59], v[146:149], v[176:179], v[56:59]
	v_mfma_f32_16x16x32_bf16 v[48:51], v[128:131], v[188:191], v[48:51]
	v_mfma_f32_16x16x32_bf16 v[40:43], v[146:149], v[188:191], v[40:43]
	v_mfma_f32_16x16x32_bf16 v[32:35], v[128:131], v[200:203], v[32:35]
	v_mfma_f32_16x16x32_bf16 v[24:27], v[146:149], v[200:203], v[24:27]
	v_mfma_f32_16x16x32_bf16 v[16:19], v[128:131], v[208:211], v[16:19]
	v_mfma_f32_16x16x32_bf16 v[8:11], v[146:149], v[208:211], v[8:11]
	v_mfma_f32_16x16x32_bf16 v[60:63], v[142:145], v[180:183], v[60:63]
	v_mfma_f32_16x16x32_bf16 v[56:59], v[150:153], v[180:183], v[56:59]
	v_mfma_f32_16x16x32_bf16 v[48:51], v[142:145], v[196:199], v[48:51]
	v_mfma_f32_16x16x32_bf16 v[40:43], v[150:153], v[196:199], v[40:43]
	v_mfma_f32_16x16x32_bf16 v[32:35], v[142:145], v[204:207], v[32:35]
	v_mfma_f32_16x16x32_bf16 v[24:27], v[150:153], v[204:207], v[24:27]
	v_mfma_f32_16x16x32_bf16 v[16:19], v[142:145], v[212:215], v[16:19]
	v_mfma_f32_16x16x32_bf16 v[8:11], v[150:153], v[212:215], v[8:11]
	v_mfma_f32_16x16x32_bf16 v[52:55], v[160:163], v[176:179], v[52:55]
	v_mfma_f32_16x16x32_bf16 v[44:47], v[168:171], v[176:179], v[44:47]
	v_mfma_f32_16x16x32_bf16 v[36:39], v[160:163], v[188:191], v[36:39]
	v_mfma_f32_16x16x32_bf16 v[28:31], v[168:171], v[188:191], v[28:31]
	v_mfma_f32_16x16x32_bf16 v[20:23], v[160:163], v[200:203], v[20:23]
	v_mfma_f32_16x16x32_bf16 v[12:15], v[168:171], v[200:203], v[12:15]
	v_mfma_f32_16x16x32_bf16 v[4:7], v[160:163], v[208:211], v[4:7]
	v_mfma_f32_16x16x32_bf16 v[0:3], v[168:171], v[208:211], v[0:3]
	v_mfma_f32_16x16x32_bf16 v[52:55], v[164:167], v[180:183], v[52:55]
	v_mfma_f32_16x16x32_bf16 v[44:47], v[172:175], v[180:183], v[44:47]
	v_mfma_f32_16x16x32_bf16 v[36:39], v[164:167], v[196:199], v[36:39]
	v_mfma_f32_16x16x32_bf16 v[28:31], v[172:175], v[196:199], v[28:31]
	v_mfma_f32_16x16x32_bf16 v[20:23], v[164:167], v[204:207], v[20:23]
	v_mfma_f32_16x16x32_bf16 v[12:15], v[172:175], v[204:207], v[12:15]
	v_mfma_f32_16x16x32_bf16 v[4:7], v[164:167], v[212:215], v[4:7]
	v_mfma_f32_16x16x32_bf16 v[0:3], v[172:175], v[212:215], v[0:3]
	s_barrier
	s_add_i32 s55, s55, 2
	s_add_u32 s34, s34, 0x100
	s_addc_u32 s35, s35, 0
	s_add_u32 s23, s23, 0x100
	s_addc_u32 s54, s54, 0
	s_cmpk_gt_u32 s55, 0x7d
	s_cbranch_scc0 .LBB0_1477
	s_and_b64 vcc, exec, s[14:15]
	s_cbranch_vccz .LBB0_1480
	s_barrier
